# in-proj epilogue 32-wide rope: the 8 cos/sin table loads of a sub-head issued together instead of pairwise behind their own waits
# speedup vs baseline: 1.0125x; 1.0002x over previous
; DI float xsum32(float x) { const unsigned u = __float_as_uint(x); const auto r2 = __builtin_amdgcn_permlane32_swap(u, u, false, false); return __uint_as_float(r2[0]) + __uint_as_float(r2[1]); }
; DI void epi_inproj(const Params& p, int l, int mtile, int n0, f32x16 (&acc)[2][4], char* smem) {
;     ...
;         } else {
; #pragma unroll
;             for (int i = 0; i < 2; ++i) {
;                 float ss = 0.f;
; #pragma unroll
;                 for (int e = 0; e < 16; ++e) ss += acc[i][j][e] * acc[i][j][e];
;                 ss = xsum32(ss);
;                 const float rstd = rsqrtf(ss * (1.f / 32.f) + EPS) * qs;
; #pragma unroll
;                 for (int q = 0; q < 4; ++q) {
;                     const float4 w4 = *(const float4*)(nwt + 8 * q + 4 * h);
;                     acc[i][j][4 * q + 0] *= rstd * w4.x; acc[i][j][4 * q + 1] *= rstd * w4.y;
;                     acc[i][j][4 * q + 2] *= rstd * w4.z; acc[i][j][4 * q + 3] *= rstd * w4.w;
;                 }
.LBB0_225:
	s_xor_b64 s[44:45], s[8:9], -1
	s_lshr_b32 s8, s47, 31
	s_ashr_i32 s9, s47, 1
	s_add_i32 s9, s9, s8
	s_mul_i32 s8, s9, 9
	s_sub_i32 s42, s50, s8
	s_xor_b64 s[28:29], s[28:29], -1
	s_lshl_b32 s8, s42, 8
	s_cmp_lt_i32 s42, 8
	s_cselect_b64 s[42:43], -1, 0
	s_and_b64 s[60:61], s[42:43], s[34:35]
	s_add_i32 s34, s58, 0xfffffc00
	s_add_i32 s35, s58, 0xfffff800
	s_min_u32 s34, s34, s35
	s_cmpk_lt_u32 s34, 0x180
	s_cselect_b64 vcc, -1, 0
	v_cndmask_b32_e32 v128, 1.0, v206, vcc
	v_and_b32_e32 v144, 0xffffff80, v145
	v_and_b32_e32 v180, 31, v145
	v_bfe_u32 v178, v145, 5, 1
	v_cndmask_b32_e64 v179, v128, v207, s[40:41]
	v_add_u32_e32 v128, s8, v144
	v_or_b32_e32 v148, v128, v180
	v_lshlrev_b32_e32 v192, 4, v178
	v_cndmask_b32_e64 v128, 0, 1, s[28:29]
	s_mov_b64 s[6:7], -1
	v_lshl_add_u64 v[146:147], s[4:5], 0, v[192:193]
	s_and_b64 vcc, exec, s[44:45]
	v_cmp_ne_u32_e64 s[40:41], 1, v128
	s_cbranch_vccz .LBB0_238
	s_mov_b64 s[4:5], -1
	s_and_b64 vcc, exec, s[40:41]
	v_mul_f32_e32 v181, v113, v113
	s_cbranch_vccnz .LBB0_234
	v_fma_f32 v134, v112, v112, v181
	v_fmac_f32_e32 v134, v114, v114
	v_fmac_f32_e32 v134, v115, v115
	v_fmac_f32_e32 v134, v116, v116
	v_fmac_f32_e32 v134, v117, v117
	v_fmac_f32_e32 v134, v118, v118
	v_fmac_f32_e32 v134, v119, v119
	v_fmac_f32_e32 v134, v120, v120
	v_fmac_f32_e32 v134, v121, v121
	v_pk_mul_f32 v[132:133], v[122:123], v[122:123]
	v_pk_mul_f32 v[130:131], v[124:125], v[124:125]
	v_add_f32_e32 v132, v132, v134
	v_add_f32_e32 v132, v133, v132
	v_add_f32_e32 v130, v130, v132
	v_pk_mul_f32 v[128:129], v[126:127], v[126:127]
	v_add_f32_e32 v130, v131, v130
	v_add_f32_e32 v128, v128, v130
	v_add_f32_e32 v128, v129, v128
	v_mov_b32_e32 v129, v128
	s_nop 1
	v_permlane32_swap_b32_e32 v128, v129
	v_add_f32_e32 v128, v128, v129
	v_fmamk_f32 v128, v128, 0x3d000000, v201
	v_cmp_gt_f32_e32 vcc, s87, v128
	v_mul_f32_e32 v129, 0x4b800000, v128
	v_ashrrev_i32_e32 v149, 31, v148
	v_cndmask_b32_e32 v128, v128, v129, vcc
	v_rsq_f32_e32 v128, v128
	v_lshlrev_b64 v[174:175], 3, v[148:149]
	v_mov_b32_e32 v168, v127
	v_mov_b32_e32 v169, v119
	v_mul_f32_e32 v129, 0x45800000, v128
	v_cndmask_b32_e32 v128, v128, v129, vcc
	v_mul_f32_e32 v166, v179, v128
	global_load_dwordx4 v[128:131], v[146:147], off offset:32
	s_and_b64 vcc, exec, s[60:61]
	s_waitcnt vmcnt(0)
	v_mul_f32_e32 v132, v130, v166
	v_mul_f32_e32 v156, v118, v132
	global_load_dwordx4 v[136:139], v[146:147], off
	global_load_dwordx4 v[132:135], v[146:147], off offset:64
	v_pk_mul_f32 v[150:151], v[128:129], v[166:167] op_sel_hi:[1,0]
	v_mov_b32_e32 v177, v131
	v_pk_mul_f32 v[162:163], v[116:117], v[150:151]
	s_waitcnt vmcnt(1)
	v_pk_mul_f32 v[140:141], v[136:137], v[166:167] op_sel_hi:[1,0]
	s_nop 0
	v_pk_mul_f32 v[160:161], v[112:113], v[140:141]
	s_waitcnt vmcnt(0)
	v_pk_mul_f32 v[140:141], v[132:133], v[166:167] op_sel_hi:[1,0]
	s_nop 0
	v_pk_mul_f32 v[152:153], v[120:121], v[140:141]
	v_pk_mul_f32 v[140:141], v[138:139], v[166:167] op_sel_hi:[1,0]
	s_nop 0
	v_pk_mul_f32 v[158:159], v[114:115], v[140:141]
	v_pk_mul_f32 v[140:141], v[166:167], v[134:135] op_sel_hi:[0,1]
	v_pk_mul_f32 v[154:155], v[122:123], v[140:141]
	global_load_dwordx4 v[140:143], v[146:147], off offset:96
	s_waitcnt vmcnt(0)
	v_mov_b32_e32 v176, v143
	v_pk_mul_f32 v[150:151], v[166:167], v[140:141] op_sel_hi:[0,1]
	v_mul_f32_e32 v149, v166, v142
	v_pk_mul_f32 v[166:167], v[166:167], v[176:177] op_sel_hi:[0,1]
	v_pk_mul_f32 v[164:165], v[124:125], v[150:151]
	v_mul_f32_e32 v150, v126, v149
	v_pk_mul_f32 v[166:167], v[168:169], v[166:167]
	s_cbranch_vccz .LBB0_229
; DI void epi_inproj(const Params& p, int l, int mtile, int n0, f32x16 (&acc)[2][4], char* smem) {
;     ...
;                 if (rope) {
;                     const float* tab = p.rope32 + (size_t)t * 2;
; #pragma unroll
;                     for (int q = 0; q < 2; ++q) {
; #pragma unroll
;                         for (int e = 0; e < 4; ++e) {
;                             const float2 cs = *(const float2*)(tab + (size_t)(8 * q + 4 * h + e) * (SEQ * 2));
;                             const float x1 = acc[i][j][4 * q + e], x2 = acc[i][j][4 * q + 8 + e];
;                             acc[i][j][4 * q + e] = x1 * cs.x - x2 * cs.y;
;                             acc[i][j][4 * q + 8 + e] = x2 * cs.x + x1 * cs.y;
;                         }
	s_load_dwordx2 s[4:5], s[0:1], 0xf0
	v_lshlrev_b32_e32 v192, 16, v178
	v_mov_b32_e32 v151, v166
	v_mov_b32_e32 v157, v167
	s_waitcnt lgkmcnt(0)
	v_lshl_add_u64 v[168:169], s[4:5], 0, v[174:175]
	v_lshl_add_u64 v[182:183], v[168:169], 0, v[192:193]
	global_load_dwordx2 v[238:239], v[182:183], off
	v_add_co_u32_e32 v240, vcc, 0x4000, v182
	v_addc_co_u32_e32 v241, vcc, 0, v183, vcc
	global_load_dwordx2 v[240:241], v[240:241], off
	v_add_co_u32_e32 v242, vcc, 0x8000, v182
	v_addc_co_u32_e32 v243, vcc, 0, v183, vcc
	global_load_dwordx2 v[242:243], v[242:243], off
	v_add_co_u32_e32 v244, vcc, 0xc000, v182
	v_addc_co_u32_e32 v245, vcc, 0, v183, vcc
	global_load_dwordx2 v[244:245], v[244:245], off
	v_add_co_u32_e32 v246, vcc, 0x20000, v182
	v_addc_co_u32_e32 v247, vcc, 0, v183, vcc
	global_load_dwordx2 v[246:247], v[246:247], off
	v_add_co_u32_e32 v248, vcc, 0x24000, v182
	v_addc_co_u32_e32 v249, vcc, 0, v183, vcc
	global_load_dwordx2 v[248:249], v[248:249], off
	v_add_co_u32_e32 v250, vcc, 0x2c000, v182
	v_addc_co_u32_e32 v251, vcc, 0, v183, vcc
	global_load_dwordx2 v[250:251], v[250:251], off
	v_add_co_u32_e32 v252, vcc, 0x28000, v182
	v_addc_co_u32_e32 v253, vcc, 0, v183, vcc
	global_load_dwordx2 v[252:253], v[252:253], off
	v_add_co_u32_e32 v170, vcc, 0x4000, v182
	s_waitcnt vmcnt(0)
	v_mov_b32_e32 v168, v238
	v_mov_b32_e32 v169, v239
	s_nop 0
	v_addc_co_u32_e32 v171, vcc, 0, v183, vcc
	v_mov_b32_e32 v170, v240
	v_mov_b32_e32 v171, v241
	s_mov_b32 s4, 0x20000
	s_waitcnt vmcnt(1)
	v_mov_b32_e32 v172, v168
	s_waitcnt vmcnt(0)
	v_mov_b32_e32 v173, v170
	v_mov_b32_e32 v170, v169
	v_pk_mul_f32 v[168:169], v[152:153], v[170:171]
	s_nop 0
	v_pk_fma_f32 v[168:169], v[160:161], v[172:173], v[168:169] neg_lo:[0,0,1] neg_hi:[0,0,1]
	v_pk_mul_f32 v[160:161], v[160:161], v[170:171]
	s_nop 0
	v_pk_fma_f32 v[152:153], v[152:153], v[172:173], v[160:161]
	v_add_co_u32_e32 v160, vcc, 0x8000, v182
	s_nop 1
	v_addc_co_u32_e32 v161, vcc, 0, v183, vcc
	v_add_co_u32_e32 v170, vcc, 0xc000, v182
	v_mov_b32_e32 v160, v242
	v_mov_b32_e32 v161, v243
	s_nop 0
	v_addc_co_u32_e32 v171, vcc, 0, v183, vcc
	v_mov_b32_e32 v172, v244
	v_mov_b32_e32 v173, v245
	s_waitcnt vmcnt(1)
	v_mov_b32_e32 v184, v160
	s_waitcnt vmcnt(0)
	v_mov_b32_e32 v185, v172
	v_mov_b32_e32 v172, v161
	v_pk_mul_f32 v[160:161], v[154:155], v[172:173]
	s_nop 0
	v_pk_fma_f32 v[170:171], v[158:159], v[184:185], v[160:161] neg_lo:[0,0,1] neg_hi:[0,0,1]
	v_pk_mul_f32 v[158:159], v[158:159], v[172:173]
	s_nop 0
	v_pk_fma_f32 v[154:155], v[154:155], v[184:185], v[158:159]
	v_add_co_u32_e32 v158, vcc, s4, v182
	s_mov_b32 s4, 0x24000
	s_nop 0
	v_addc_co_u32_e32 v159, vcc, 0, v183, vcc
	v_add_co_u32_e32 v160, vcc, s4, v182
	v_mov_b32_e32 v158, v246
	v_mov_b32_e32 v159, v247
	s_nop 0
	v_addc_co_u32_e32 v161, vcc, 0, v183, vcc
	v_mov_b32_e32 v160, v248
	v_mov_b32_e32 v161, v249
	s_mov_b32 s4, 0x2c000
	s_waitcnt vmcnt(1)
	v_mov_b32_e32 v184, v158
	s_waitcnt vmcnt(0)
	v_mov_b32_e32 v185, v160
	v_mov_b32_e32 v160, v159
	v_pk_mul_f32 v[158:159], v[164:165], v[160:161]
	s_nop 0
	v_pk_fma_f32 v[172:173], v[162:163], v[184:185], v[158:159] neg_lo:[0,0,1] neg_hi:[0,0,1]
	v_pk_mul_f32 v[158:159], v[162:163], v[160:161]
	s_nop 0
	v_pk_fma_f32 v[164:165], v[164:165], v[184:185], v[158:159]
	v_add_co_u32_e32 v158, vcc, s4, v182
	s_mov_b32 s4, 0x28000
	s_nop 0
	v_addc_co_u32_e32 v159, vcc, 0, v183, vcc
	v_add_co_u32_e32 v160, vcc, s4, v182
	v_mov_b32_e32 v158, v250
	v_mov_b32_e32 v159, v251
	s_nop 0
	v_addc_co_u32_e32 v161, vcc, 0, v183, vcc
	v_mov_b32_e32 v160, v252
	v_mov_b32_e32 v161, v253
	s_waitcnt vmcnt(1)
	v_mov_b32_e32 v183, v159
	v_mov_b32_e32 v163, v158
	v_pk_mul_f32 v[158:159], v[166:167], v[158:159]
	s_waitcnt vmcnt(0)
	v_mov_b32_e32 v182, v161
	v_mov_b32_e32 v162, v160
	v_pk_mul_f32 v[182:183], v[150:151], v[182:183]
	v_mul_f32_e32 v150, v150, v160
	v_pk_fma_f32 v[182:183], v[156:157], v[162:163], v[182:183] neg_lo:[0,0,1] neg_hi:[0,0,1]
	v_mul_f32_e32 v156, v156, v161
	v_mov_b32_e32 v151, v158
	v_mov_b32_e32 v157, v159
	v_pk_add_f32 v[150:151], v[150:151], v[156:157]
	v_mov_b32_e32 v160, v168
	v_mov_b32_e32 v161, v169
	v_mov_b32_e32 v158, v170
	v_mov_b32_e32 v159, v171
	v_mov_b32_e32 v162, v172
	v_mov_b32_e32 v163, v173
	v_mov_b32_e32 v156, v182
	v_mov_b32_e32 v157, v183
	s_branch .LBB0_230

; DI float xsum32(float x) { const unsigned u = __float_as_uint(x); const auto r2 = __builtin_amdgcn_permlane32_swap(u, u, false, false); return __uint_as_float(r2[0]) + __uint_as_float(r2[1]); }
; DI void epi_inproj(const Params& p, int l, int mtile, int n0, f32x16 (&acc)[2][4], char* smem) {
;     ...
;             for (int i = 0; i < 2; ++i) {
;                 float ss = 0.f;
; #pragma unroll
;                 for (int e = 0; e < 16; ++e) ss += acc[i][j][e] * acc[i][j][e];
;                 ss = xsum32(ss);
;                 const float rstd = rsqrtf(ss * (1.f / 32.f) + EPS) * qs;
; #pragma unroll
;                 for (int q = 0; q < 4; ++q) {
;                     const float4 w4 = *(const float4*)(nwt + 8 * q + 4 * h);
;                     acc[i][j][4 * q + 0] *= rstd * w4.x; acc[i][j][4 * q + 1] *= rstd * w4.y;
;                     acc[i][j][4 * q + 2] *= rstd * w4.z; acc[i][j][4 * q + 3] *= rstd * w4.w;
;                 }
;                 if (rope) {
;                     const float* tab = p.rope32 + (size_t)t * 2;
; #pragma unroll
;                     for (int q = 0; q < 2; ++q) {
; #pragma unroll
;                         for (int e = 0; e < 4; ++e) {
;                             const float2 cs = *(const float2*)(tab + (size_t)(8 * q + 4 * h + e) * (SEQ * 2));
;                             const float x1 = acc[i][j][4 * q + e], x2 = acc[i][j][4 * q + 8 + e];
;                             acc[i][j][4 * q + e] = x1 * cs.x - x2 * cs.y;
;                             acc[i][j][4 * q + 8 + e] = x2 * cs.x + x1 * cs.y;
;                         }
.LBB0_230:
	v_mul_f32_e32 v131, v97, v97
	v_fmac_f32_e32 v131, v96, v96
	v_fmac_f32_e32 v131, v98, v98
	v_fmac_f32_e32 v131, v99, v99
	v_fmac_f32_e32 v131, v100, v100
	v_fmac_f32_e32 v131, v101, v101
	v_fmac_f32_e32 v131, v102, v102
	v_fmac_f32_e32 v131, v103, v103
	v_fmac_f32_e32 v131, v104, v104
	v_fmac_f32_e32 v131, v105, v105
	v_pk_mul_f32 v[170:171], v[106:107], v[106:107]
	v_pk_mul_f32 v[168:169], v[108:109], v[108:109]
	v_add_f32_e32 v131, v170, v131
	v_add_f32_e32 v131, v171, v131
	v_add_f32_e32 v131, v168, v131
	v_pk_mul_f32 v[166:167], v[110:111], v[110:111]
	v_add_f32_e32 v131, v169, v131
	v_add_f32_e32 v131, v166, v131
	v_add_f32_e32 v131, v167, v131
	v_mov_b32_e32 v143, v131
	s_nop 1
	v_permlane32_swap_b32_e32 v131, v143
	v_add_f32_e32 v131, v131, v143
	v_fmamk_f32 v131, v131, 0x3d000000, v201
	v_mul_f32_e32 v143, 0x4b800000, v131
	v_cmp_gt_f32_e32 vcc, s87, v131
	s_nop 1
	v_cndmask_b32_e32 v131, v131, v143, vcc
	v_rsq_f32_e32 v131, v131
	s_nop 0
	v_mul_f32_e32 v143, 0x45800000, v131
	v_cndmask_b32_e32 v131, v131, v143, vcc
	v_mul_f32_e32 v182, v179, v131
	v_mul_f32_e32 v130, v130, v182
	v_mul_f32_e32 v166, v102, v130
	v_pk_mul_f32 v[130:131], v[136:137], v[182:183] op_sel_hi:[1,0]
	v_pk_mul_f32 v[128:129], v[128:129], v[182:183] op_sel_hi:[1,0]
	v_pk_mul_f32 v[172:173], v[96:97], v[130:131]
	v_pk_mul_f32 v[130:131], v[132:133], v[182:183] op_sel_hi:[1,0]
	s_andn2_b64 vcc, exec, s[60:61]
	v_pk_mul_f32 v[168:169], v[104:105], v[130:131]
	v_pk_mul_f32 v[130:131], v[138:139], v[182:183] op_sel_hi:[1,0]
	v_pk_mul_f32 v[138:139], v[100:101], v[128:129]
	v_pk_mul_f32 v[170:171], v[98:99], v[130:131]
	v_pk_mul_f32 v[130:131], v[134:135], v[182:183] op_sel_hi:[1,0]
	v_pk_mul_f32 v[128:129], v[140:141], v[182:183] op_sel_hi:[1,0]
	v_pk_mul_f32 v[136:137], v[106:107], v[130:131]
	v_mul_f32_e32 v130, v142, v182
	v_mul_f32_e32 v132, v110, v130
	v_pk_mul_f32 v[130:131], v[176:177], v[182:183] op_sel_hi:[1,0]
	v_mov_b32_e32 v134, v111
	v_mov_b32_e32 v135, v103
	v_pk_mul_f32 v[128:129], v[108:109], v[128:129]
	v_pk_mul_f32 v[134:135], v[134:135], v[130:131]
	s_cbranch_vccnz .LBB0_232
	s_load_dwordx2 s[4:5], s[0:1], 0xf0
	v_lshlrev_b32_e32 v192, 16, v178
	v_mov_b32_e32 v133, v134
	v_mov_b32_e32 v167, v135
	s_waitcnt lgkmcnt(0)
	v_lshl_add_u64 v[130:131], s[4:5], 0, v[174:175]
	v_lshl_add_u64 v[140:141], v[130:131], 0, v[192:193]
	global_load_dwordx2 v[238:239], v[140:141], off
	v_add_co_u32_e32 v240, vcc, 0x4000, v140
	v_addc_co_u32_e32 v241, vcc, 0, v141, vcc
	global_load_dwordx2 v[240:241], v[240:241], off
	v_add_co_u32_e32 v242, vcc, 0x8000, v140
	v_addc_co_u32_e32 v243, vcc, 0, v141, vcc
	global_load_dwordx2 v[242:243], v[242:243], off
	v_add_co_u32_e32 v244, vcc, 0xc000, v140
	v_addc_co_u32_e32 v245, vcc, 0, v141, vcc
	global_load_dwordx2 v[244:245], v[244:245], off
	v_add_co_u32_e32 v246, vcc, 0x20000, v140
	v_addc_co_u32_e32 v247, vcc, 0, v141, vcc
	global_load_dwordx2 v[246:247], v[246:247], off
	v_add_co_u32_e32 v248, vcc, 0x24000, v140
	v_addc_co_u32_e32 v249, vcc, 0, v141, vcc
	global_load_dwordx2 v[248:249], v[248:249], off
	v_add_co_u32_e32 v250, vcc, 0x2c000, v140
	v_addc_co_u32_e32 v251, vcc, 0, v141, vcc
	global_load_dwordx2 v[250:251], v[250:251], off
	v_add_co_u32_e32 v252, vcc, 0x28000, v140
	v_addc_co_u32_e32 v253, vcc, 0, v141, vcc
	global_load_dwordx2 v[252:253], v[252:253], off
	v_add_co_u32_e32 v142, vcc, 0x4000, v140
	s_waitcnt vmcnt(0)
	v_mov_b32_e32 v130, v238
	v_mov_b32_e32 v131, v239
	s_nop 0
	v_addc_co_u32_e32 v143, vcc, 0, v141, vcc
	v_mov_b32_e32 v142, v240
	v_mov_b32_e32 v143, v241
	s_mov_b32 s4, 0x20000
	s_waitcnt vmcnt(1)
	v_mov_b32_e32 v174, v130
	s_waitcnt vmcnt(0)
	v_mov_b32_e32 v175, v142
	v_mov_b32_e32 v142, v131
	v_pk_mul_f32 v[130:131], v[168:169], v[142:143]
	v_pk_mul_f32 v[142:143], v[172:173], v[142:143]
	v_pk_fma_f32 v[130:131], v[172:173], v[174:175], v[130:131] neg_lo:[0,0,1] neg_hi:[0,0,1]
	v_pk_fma_f32 v[168:169], v[168:169], v[174:175], v[142:143]
	v_add_co_u32_e32 v142, vcc, 0x8000, v140
	s_nop 1
	v_addc_co_u32_e32 v143, vcc, 0, v141, vcc
	v_add_co_u32_e32 v172, vcc, 0xc000, v140
	v_mov_b32_e32 v142, v242
	v_mov_b32_e32 v143, v243
	s_nop 0
	v_addc_co_u32_e32 v173, vcc, 0, v141, vcc
	v_mov_b32_e32 v172, v244
	v_mov_b32_e32 v173, v245
	s_waitcnt vmcnt(1)
	v_mov_b32_e32 v174, v142
	s_waitcnt vmcnt(0)
	v_mov_b32_e32 v175, v172
	v_mov_b32_e32 v172, v143
	v_pk_mul_f32 v[142:143], v[136:137], v[172:173]
	s_nop 0
	v_pk_fma_f32 v[142:143], v[170:171], v[174:175], v[142:143] neg_lo:[0,0,1] neg_hi:[0,0,1]
	v_pk_mul_f32 v[170:171], v[170:171], v[172:173]
	s_nop 0
	v_pk_fma_f32 v[136:137], v[136:137], v[174:175], v[170:171]
	v_add_co_u32_e32 v170, vcc, s4, v140
	s_mov_b32 s4, 0x24000
	s_nop 0
	v_addc_co_u32_e32 v171, vcc, 0, v141, vcc
	v_add_co_u32_e32 v172, vcc, s4, v140
	v_mov_b32_e32 v170, v246
	v_mov_b32_e32 v171, v247
	s_nop 0
	v_addc_co_u32_e32 v173, vcc, 0, v141, vcc
	v_mov_b32_e32 v172, v248
	v_mov_b32_e32 v173, v249
	s_mov_b32 s4, 0x2c000
	s_waitcnt vmcnt(1)
	v_mov_b32_e32 v174, v170
	s_waitcnt vmcnt(0)
	v_mov_b32_e32 v175, v172
	v_mov_b32_e32 v172, v171
	v_pk_mul_f32 v[170:171], v[128:129], v[172:173]
	s_nop 0
	v_pk_fma_f32 v[170:171], v[138:139], v[174:175], v[170:171] neg_lo:[0,0,1] neg_hi:[0,0,1]
	v_pk_mul_f32 v[138:139], v[138:139], v[172:173]
	s_nop 0
	v_pk_fma_f32 v[128:129], v[128:129], v[174:175], v[138:139]
	v_add_co_u32_e32 v138, vcc, s4, v140
	s_mov_b32 s4, 0x28000
	s_nop 0
	v_addc_co_u32_e32 v139, vcc, 0, v141, vcc
	v_add_co_u32_e32 v140, vcc, s4, v140
	v_mov_b32_e32 v138, v250
	v_mov_b32_e32 v139, v251
	s_nop 0
	v_addc_co_u32_e32 v141, vcc, 0, v141, vcc
	v_mov_b32_e32 v140, v252
	v_mov_b32_e32 v141, v253
	s_waitcnt vmcnt(1)
	v_mov_b32_e32 v175, v139
	v_mov_b32_e32 v173, v138
	v_pk_mul_f32 v[134:135], v[134:135], v[138:139]
	s_waitcnt vmcnt(0)
	v_mov_b32_e32 v174, v141
	v_mov_b32_e32 v172, v140
	v_pk_mul_f32 v[174:175], v[132:133], v[174:175]
	v_mul_f32_e32 v132, v132, v140
	v_pk_fma_f32 v[172:173], v[166:167], v[172:173], v[174:175] neg_lo:[0,0,1] neg_hi:[0,0,1]
	v_mul_f32_e32 v140, v166, v141
	v_mov_b32_e32 v133, v134
	v_mov_b32_e32 v141, v135
	v_pk_add_f32 v[132:133], v[132:133], v[140:141]
	v_mov_b32_e32 v167, v173
	v_mov_b32_e32 v166, v172
	v_mov_b32_e32 v139, v171
	v_mov_b32_e32 v138, v170
	v_mov_b32_e32 v171, v143
	v_mov_b32_e32 v170, v142
	v_mov_b32_e32 v173, v131
	v_mov_b32_e32 v172, v130
	s_branch .LBB0_233

; DI unsigned pk2(float a, float b) { f2_t v = {a, b}; bf2_t r = __builtin_convertvector(v, bf2_t); return __builtin_bit_cast(unsigned, r); }
; DI float xsum32(float x) { const unsigned u = __float_as_uint(x); const auto r2 = __builtin_amdgcn_permlane32_swap(u, u, false, false); return __uint_as_float(r2[0]) + __uint_as_float(r2[1]); }
; DI void epi_inproj(const Params& p, int l, int mtile, int n0, f32x16 (&acc)[2][4], char* smem) {
;     ...
;             for (int i = 0; i < 2; ++i) {
;                 float ss = 0.f;
; #pragma unroll
;                 for (int e = 0; e < 16; ++e) ss += acc[i][j][e] * acc[i][j][e];
;                 ss = xsum32(ss);
;                 const float rstd = rsqrtf(ss * (1.f / 32.f) + EPS) * qs;
; #pragma unroll
;                 for (int q = 0; q < 4; ++q) {
;                     const float4 w4 = *(const float4*)(nwt + 8 * q + 4 * h);
;                     acc[i][j][4 * q + 0] *= rstd * w4.x; acc[i][j][4 * q + 1] *= rstd * w4.y;
;                     acc[i][j][4 * q + 2] *= rstd * w4.z; acc[i][j][4 * q + 3] *= rstd * w4.w;
;                 }
;     ...
; #pragma unroll
;         for (int i = 0; i < 2; ++i)
; #pragma unroll
;             for (int q = 0; q < 4; ++q) {
;                 uint2 o; o.x = pk2(acc[i][j][4 * q], acc[i][j][4 * q + 1]); o.y = pk2(acc[i][j][4 * q + 2], acc[i][j][4 * q + 3]);
;                 stage_quad_bf16(sb, 32 * j + r, 4 * i + q, h, o);
;             }
.LBB0_240:
	v_lshlrev_b32_e32 v96, 8, v145
	v_and_b32_e32 v96, 0xffffc000, v96
	v_add_u32_e32 v149, 32, v96
	v_lshlrev_b32_e32 v96, 3, v178
	v_lshlrev_b32_e32 v97, 7, v180
	v_lshlrev_b32_e32 v99, 4, v145
	v_add3_u32 v98, v149, v96, v97
	v_and_b32_e32 v100, 0x70, v99
	v_cvt_pk_bf16_f32 v96, v160, v161
	v_cvt_pk_bf16_f32 v97, v158, v159
	v_add_u32_e32 v158, v98, v100
	v_bitop3_b32 v100, v99, 16, v208 bitop3:0x6c
	ds_write_b64 v158, v[96:97]
	v_cvt_pk_bf16_f32 v96, v162, v163
	v_cvt_pk_bf16_f32 v97, v156, v157
	v_add_u32_e32 v156, v98, v100
	v_bitop3_b32 v100, v99, 32, v208 bitop3:0x6c
	ds_write_b64 v156, v[96:97]
	v_cvt_pk_bf16_f32 v96, v152, v153
	v_cvt_pk_bf16_f32 v97, v154, v155
	v_add_u32_e32 v152, v98, v100
	v_bitop3_b32 v100, v99, 48, v208 bitop3:0x6c
	ds_write_b64 v152, v[96:97]
	v_cvt_pk_bf16_f32 v96, v164, v165
	v_cvt_pk_bf16_f32 v97, v150, v151
	v_add_u32_e32 v150, v98, v100
	v_bitop3_b32 v100, v99, 64, v208 bitop3:0x6c
	s_movk_i32 s4, 0x50
	ds_write_b64 v150, v[96:97]
	v_cvt_pk_bf16_f32 v96, v172, v173
	v_cvt_pk_bf16_f32 v97, v170, v171
	v_add_u32_e32 v151, v98, v100
	v_bitop3_b32 v100, v99, s4, v208 bitop3:0x6c
	s_movk_i32 s4, 0x60
	ds_write_b64 v151, v[96:97]
	v_cvt_pk_bf16_f32 v96, v138, v139
	v_cvt_pk_bf16_f32 v97, v166, v167
	v_add_u32_e32 v153, v98, v100
	v_bitop3_b32 v100, v99, s4, v208 bitop3:0x6c
	s_movk_i32 s4, 0x70
	ds_write_b64 v153, v[96:97]
	v_cvt_pk_bf16_f32 v96, v168, v169
	v_cvt_pk_bf16_f32 v97, v136, v137
	v_add_u32_e32 v154, v98, v100
	v_bitop3_b32 v99, v99, s4, v99 bitop3:0xc
	ds_write_b64 v154, v[96:97]
	v_cvt_pk_bf16_f32 v96, v128, v129
	v_cvt_pk_bf16_f32 v97, v132, v133
	v_add_u32_e32 v155, v98, v99
	ds_write_b64 v155, v[96:97]
	v_cndmask_b32_e64 v96, 0, 1, s[44:45]
	v_cmp_ne_u32_e64 s[42:43], 1, v96
	s_andn2_b64 vcc, exec, s[44:45]
	s_mov_b64 s[4:5], -1
	s_cbranch_vccnz .LBB0_254
	v_or_b32_e32 v126, 32, v148
	s_and_b64 vcc, exec, s[40:41]
	v_mul_f32_e32 v157, v81, v81
	s_cbranch_vccnz .LBB0_247
	v_fma_f32 v102, v80, v80, v157
	v_fmac_f32_e32 v102, v82, v82
	v_fmac_f32_e32 v102, v83, v83
	v_fmac_f32_e32 v102, v84, v84
	v_fmac_f32_e32 v102, v85, v85
	v_fmac_f32_e32 v102, v86, v86
	v_fmac_f32_e32 v102, v87, v87
	v_fmac_f32_e32 v102, v88, v88
	v_fmac_f32_e32 v102, v89, v89
	v_pk_mul_f32 v[100:101], v[90:91], v[90:91]
	v_pk_mul_f32 v[98:99], v[92:93], v[92:93]
	v_add_f32_e32 v100, v100, v102
	v_add_f32_e32 v100, v101, v100
	v_add_f32_e32 v98, v98, v100
	v_pk_mul_f32 v[96:97], v[94:95], v[94:95]
	v_add_f32_e32 v98, v99, v98
	v_add_f32_e32 v96, v96, v98
	v_add_f32_e32 v96, v97, v96
	v_mov_b32_e32 v97, v96
	s_nop 1
	v_permlane32_swap_b32_e32 v96, v97
	v_add_f32_e32 v96, v96, v97
	v_fmamk_f32 v96, v96, 0x3d000000, v201
	v_cmp_gt_f32_e32 vcc, s87, v96
	v_mul_f32_e32 v97, 0x4b800000, v96
	v_ashrrev_i32_e32 v127, 31, v126
	v_cndmask_b32_e32 v96, v96, v97, vcc
	v_rsq_f32_e32 v96, v96
	v_mov_b32_e32 v132, v95
	v_mov_b32_e32 v133, v87
	v_lshlrev_b64 v[140:141], 3, v[126:127]
	v_mul_f32_e32 v97, 0x45800000, v96
	v_cndmask_b32_e32 v96, v96, v97, vcc
	v_mul_f32_e32 v130, v179, v96
	global_load_dwordx4 v[96:99], v[146:147], off offset:32
	s_andn2_b64 vcc, exec, s[60:61]
	s_waitcnt vmcnt(0)
	v_mul_f32_e32 v100, v98, v130
	v_mul_f32_e32 v118, v86, v100
	global_load_dwordx4 v[104:107], v[146:147], off
	global_load_dwordx4 v[100:103], v[146:147], off offset:64
	v_pk_mul_f32 v[112:113], v[96:97], v[130:131] op_sel_hi:[1,0]
	v_mov_b32_e32 v143, v99
	v_pk_mul_f32 v[124:125], v[84:85], v[112:113]
	v_cndmask_b32_e64 v99, 0, 1, s[60:61]
	v_cmp_ne_u32_e64 s[44:45], 1, v99
	s_waitcnt vmcnt(1)
	v_pk_mul_f32 v[108:109], v[104:105], v[130:131] op_sel_hi:[1,0]
	s_nop 0
	v_pk_mul_f32 v[122:123], v[80:81], v[108:109]
	s_waitcnt vmcnt(0)
	v_pk_mul_f32 v[108:109], v[100:101], v[130:131] op_sel_hi:[1,0]
	s_nop 0
	v_pk_mul_f32 v[114:115], v[88:89], v[108:109]
	v_pk_mul_f32 v[108:109], v[106:107], v[130:131] op_sel_hi:[1,0]
	s_nop 0
	v_pk_mul_f32 v[120:121], v[82:83], v[108:109]
	v_pk_mul_f32 v[108:109], v[130:131], v[102:103] op_sel_hi:[0,1]
	v_pk_mul_f32 v[116:117], v[90:91], v[108:109]
	global_load_dwordx4 v[108:111], v[146:147], off offset:96
	s_waitcnt vmcnt(0)
	v_pk_mul_f32 v[112:113], v[130:131], v[108:109] op_sel_hi:[0,1]
	v_mov_b32_e32 v142, v111
	v_pk_mul_f32 v[128:129], v[92:93], v[112:113]
	v_mul_f32_e32 v112, v130, v110
	v_pk_mul_f32 v[130:131], v[130:131], v[142:143] op_sel_hi:[0,1]
	v_mul_f32_e32 v112, v94, v112
	v_pk_mul_f32 v[136:137], v[132:133], v[130:131]
	s_cbranch_vccnz .LBB0_244
; DI void epi_inproj(const Params& p, int l, int mtile, int n0, f32x16 (&acc)[2][4], char* smem) {
;     ...
;                 if (rope) {
;                     const float* tab = p.rope32 + (size_t)t * 2;
; #pragma unroll
;                     for (int q = 0; q < 2; ++q) {
; #pragma unroll
;                         for (int e = 0; e < 4; ++e) {
;                             const float2 cs = *(const float2*)(tab + (size_t)(8 * q + 4 * h + e) * (SEQ * 2));
;                             const float x1 = acc[i][j][4 * q + e], x2 = acc[i][j][4 * q + 8 + e];
;                             acc[i][j][4 * q + e] = x1 * cs.x - x2 * cs.y;
;                             acc[i][j][4 * q + 8 + e] = x2 * cs.x + x1 * cs.y;
;                         }
	s_load_dwordx2 s[4:5], s[0:1], 0xf0
	v_lshlrev_b32_e32 v192, 16, v178
	v_mov_b32_e32 v113, v136
	v_mov_b32_e32 v119, v137
	s_waitcnt lgkmcnt(0)
	v_lshl_add_u64 v[130:131], s[4:5], 0, v[140:141]
	v_lshl_add_u64 v[138:139], v[130:131], 0, v[192:193]
	global_load_dwordx2 v[238:239], v[138:139], off
	v_add_co_u32_e32 v240, vcc, 0x4000, v138
	v_addc_co_u32_e32 v241, vcc, 0, v139, vcc
	global_load_dwordx2 v[240:241], v[240:241], off
	v_add_co_u32_e32 v242, vcc, 0x8000, v138
	v_addc_co_u32_e32 v243, vcc, 0, v139, vcc
	global_load_dwordx2 v[242:243], v[242:243], off
	v_add_co_u32_e32 v244, vcc, 0xc000, v138
	v_addc_co_u32_e32 v245, vcc, 0, v139, vcc
	global_load_dwordx2 v[244:245], v[244:245], off
	v_add_co_u32_e32 v246, vcc, 0x20000, v138
	v_addc_co_u32_e32 v247, vcc, 0, v139, vcc
	global_load_dwordx2 v[246:247], v[246:247], off
	v_add_co_u32_e32 v248, vcc, 0x24000, v138
	v_addc_co_u32_e32 v249, vcc, 0, v139, vcc
	global_load_dwordx2 v[248:249], v[248:249], off
	v_add_co_u32_e32 v250, vcc, 0x2c000, v138
	v_addc_co_u32_e32 v251, vcc, 0, v139, vcc
	global_load_dwordx2 v[250:251], v[250:251], off
	v_add_co_u32_e32 v252, vcc, 0x28000, v138
	v_addc_co_u32_e32 v253, vcc, 0, v139, vcc
	global_load_dwordx2 v[252:253], v[252:253], off
	v_add_co_u32_e32 v132, vcc, 0x4000, v138
	s_waitcnt vmcnt(0)
	v_mov_b32_e32 v130, v238
	v_mov_b32_e32 v131, v239
	s_nop 0
	v_addc_co_u32_e32 v133, vcc, 0, v139, vcc
	v_mov_b32_e32 v132, v240
	v_mov_b32_e32 v133, v241
	s_mov_b32 s4, 0x20000
	s_waitcnt vmcnt(1)
	v_mov_b32_e32 v134, v130
	s_waitcnt vmcnt(0)
	v_mov_b32_e32 v135, v132
	v_mov_b32_e32 v132, v131
	v_pk_mul_f32 v[130:131], v[114:115], v[132:133]
	s_nop 0
	v_pk_fma_f32 v[130:131], v[122:123], v[134:135], v[130:131] neg_lo:[0,0,1] neg_hi:[0,0,1]
	v_pk_mul_f32 v[122:123], v[122:123], v[132:133]
	s_nop 0
	v_pk_fma_f32 v[114:115], v[114:115], v[134:135], v[122:123]
	v_add_co_u32_e32 v122, vcc, 0x8000, v138
	s_nop 1
	v_addc_co_u32_e32 v123, vcc, 0, v139, vcc
	v_add_co_u32_e32 v132, vcc, 0xc000, v138
	v_mov_b32_e32 v122, v242
	v_mov_b32_e32 v123, v243
	s_nop 0
	v_addc_co_u32_e32 v133, vcc, 0, v139, vcc
	v_mov_b32_e32 v134, v244
	v_mov_b32_e32 v135, v245
	s_waitcnt vmcnt(1)
	v_mov_b32_e32 v160, v122
	s_waitcnt vmcnt(0)
	v_mov_b32_e32 v161, v134
	v_mov_b32_e32 v134, v123
	v_pk_mul_f32 v[122:123], v[116:117], v[134:135]
	s_nop 0
	v_pk_fma_f32 v[132:133], v[120:121], v[160:161], v[122:123] neg_lo:[0,0,1] neg_hi:[0,0,1]
	v_pk_mul_f32 v[120:121], v[120:121], v[134:135]
	s_nop 0
	v_pk_fma_f32 v[116:117], v[116:117], v[160:161], v[120:121]
	v_add_co_u32_e32 v120, vcc, s4, v138
	s_mov_b32 s4, 0x24000
	s_nop 0
	v_addc_co_u32_e32 v121, vcc, 0, v139, vcc
	v_add_co_u32_e32 v122, vcc, s4, v138
	v_mov_b32_e32 v120, v246
	v_mov_b32_e32 v121, v247
	s_nop 0
	v_addc_co_u32_e32 v123, vcc, 0, v139, vcc
	v_mov_b32_e32 v122, v248
	v_mov_b32_e32 v123, v249
	s_mov_b32 s4, 0x2c000
	s_waitcnt vmcnt(1)
	v_mov_b32_e32 v160, v120
	s_waitcnt vmcnt(0)
	v_mov_b32_e32 v161, v122
	v_mov_b32_e32 v122, v121
	v_pk_mul_f32 v[120:121], v[128:129], v[122:123]
	s_nop 0
	v_pk_fma_f32 v[134:135], v[124:125], v[160:161], v[120:121] neg_lo:[0,0,1] neg_hi:[0,0,1]
	v_pk_mul_f32 v[120:121], v[124:125], v[122:123]
	s_nop 0
	v_pk_fma_f32 v[128:129], v[128:129], v[160:161], v[120:121]
	v_add_co_u32_e32 v120, vcc, s4, v138
	s_mov_b32 s4, 0x28000
	s_nop 0
	v_addc_co_u32_e32 v121, vcc, 0, v139, vcc
	v_add_co_u32_e32 v122, vcc, s4, v138
	v_mov_b32_e32 v120, v250
	v_mov_b32_e32 v121, v251
	s_nop 0
	v_addc_co_u32_e32 v123, vcc, 0, v139, vcc
	v_mov_b32_e32 v122, v252
	v_mov_b32_e32 v123, v253
	s_waitcnt vmcnt(1)
	v_mov_b32_e32 v139, v121
	v_mov_b32_e32 v125, v120
	v_pk_mul_f32 v[120:121], v[136:137], v[120:121]
	s_waitcnt vmcnt(0)
	v_mov_b32_e32 v138, v123
	v_mov_b32_e32 v124, v122
	v_pk_mul_f32 v[138:139], v[112:113], v[138:139]
	v_mul_f32_e32 v112, v112, v122
	v_pk_fma_f32 v[138:139], v[118:119], v[124:125], v[138:139] neg_lo:[0,0,1] neg_hi:[0,0,1]
	v_mul_f32_e32 v118, v118, v123
	v_mov_b32_e32 v113, v120
	v_mov_b32_e32 v119, v121
	v_pk_add_f32 v[112:113], v[112:113], v[118:119]
	v_mov_b32_e32 v122, v130
	v_mov_b32_e32 v123, v131
	v_mov_b32_e32 v120, v132
	v_mov_b32_e32 v121, v133
	v_mov_b32_e32 v124, v134
	v_mov_b32_e32 v125, v135
	v_mov_b32_e32 v118, v138
	v_mov_b32_e32 v137, v139
	v_mov_b32_e32 v136, v113
; DI float xsum32(float x) { const unsigned u = __float_as_uint(x); const auto r2 = __builtin_amdgcn_permlane32_swap(u, u, false, false); return __uint_as_float(r2[0]) + __uint_as_float(r2[1]); }
; DI void epi_inproj(const Params& p, int l, int mtile, int n0, f32x16 (&acc)[2][4], char* smem) {
;     ...
;             for (int i = 0; i < 2; ++i) {
;                 float ss = 0.f;
; #pragma unroll
;                 for (int e = 0; e < 16; ++e) ss += acc[i][j][e] * acc[i][j][e];
;                 ss = xsum32(ss);
;                 const float rstd = rsqrtf(ss * (1.f / 32.f) + EPS) * qs;
; #pragma unroll
;                 for (int q = 0; q < 4; ++q) {
;                     const float4 w4 = *(const float4*)(nwt + 8 * q + 4 * h);
;                     acc[i][j][4 * q + 0] *= rstd * w4.x; acc[i][j][4 * q + 1] *= rstd * w4.y;
;                     acc[i][j][4 * q + 2] *= rstd * w4.z; acc[i][j][4 * q + 3] *= rstd * w4.w;
;                 }
;                 if (rope) {
;                     const float* tab = p.rope32 + (size_t)t * 2;
; #pragma unroll
;                     for (int q = 0; q < 2; ++q) {
; #pragma unroll
;                         for (int e = 0; e < 4; ++e) {
;                             const float2 cs = *(const float2*)(tab + (size_t)(8 * q + 4 * h + e) * (SEQ * 2));
;                             const float x1 = acc[i][j][4 * q + e], x2 = acc[i][j][4 * q + 8 + e];
;                             acc[i][j][4 * q + e] = x1 * cs.x - x2 * cs.y;
;                             acc[i][j][4 * q + 8 + e] = x2 * cs.x + x1 * cs.y;
;                         }
.LBB0_244:
	v_mul_f32_e32 v99, v65, v65
	v_fmac_f32_e32 v99, v64, v64
	v_fmac_f32_e32 v99, v66, v66
	v_fmac_f32_e32 v99, v67, v67
	v_fmac_f32_e32 v99, v68, v68
	v_fmac_f32_e32 v99, v69, v69
	v_fmac_f32_e32 v99, v70, v70
	v_fmac_f32_e32 v99, v71, v71
	v_fmac_f32_e32 v99, v72, v72
	v_fmac_f32_e32 v99, v73, v73
	v_pk_mul_f32 v[134:135], v[74:75], v[74:75]
	v_pk_mul_f32 v[132:133], v[76:77], v[76:77]
	v_add_f32_e32 v99, v134, v99
	v_add_f32_e32 v99, v135, v99
	v_add_f32_e32 v99, v132, v99
	v_pk_mul_f32 v[130:131], v[78:79], v[78:79]
	v_add_f32_e32 v99, v133, v99
	v_add_f32_e32 v99, v130, v99
	v_add_f32_e32 v99, v131, v99
	v_mov_b32_e32 v111, v99
	s_nop 1
	v_permlane32_swap_b32_e32 v99, v111
	v_add_f32_e32 v99, v99, v111
	v_fmamk_f32 v99, v99, 0x3d000000, v201
	v_mul_f32_e32 v111, 0x4b800000, v99
	v_cmp_gt_f32_e32 vcc, s87, v99
	s_nop 1
	v_cndmask_b32_e32 v99, v99, v111, vcc
	v_rsq_f32_e32 v99, v99
	s_nop 0
	v_mul_f32_e32 v111, 0x45800000, v99
	v_cndmask_b32_e32 v99, v99, v111, vcc
	v_mul_f32_e32 v160, v179, v99
	v_mul_f32_e32 v98, v98, v160
	v_mul_f32_e32 v130, v70, v98
	v_pk_mul_f32 v[98:99], v[104:105], v[160:161] op_sel_hi:[1,0]
	v_pk_mul_f32 v[96:97], v[96:97], v[160:161] op_sel_hi:[1,0]
	v_pk_mul_f32 v[138:139], v[64:65], v[98:99]
	v_pk_mul_f32 v[98:99], v[100:101], v[160:161] op_sel_hi:[1,0]
	v_pk_mul_f32 v[132:133], v[68:69], v[96:97]
	v_pk_mul_f32 v[104:105], v[72:73], v[98:99]
	v_pk_mul_f32 v[98:99], v[106:107], v[160:161] op_sel_hi:[1,0]
	v_pk_mul_f32 v[96:97], v[108:109], v[160:161] op_sel_hi:[1,0]
	v_pk_mul_f32 v[134:135], v[66:67], v[98:99]
	v_pk_mul_f32 v[98:99], v[102:103], v[160:161] op_sel_hi:[1,0]
	v_mov_b32_e32 v102, v79
	v_pk_mul_f32 v[106:107], v[74:75], v[98:99]
	v_mul_f32_e32 v98, v110, v160
	v_mul_f32_e32 v100, v78, v98
	v_pk_mul_f32 v[98:99], v[142:143], v[160:161] op_sel_hi:[1,0]
	v_mov_b32_e32 v103, v71
	v_pk_mul_f32 v[96:97], v[76:77], v[96:97]
	s_and_b64 vcc, exec, s[44:45]
	v_pk_mul_f32 v[98:99], v[102:103], v[98:99]
	s_cbranch_vccnz .LBB0_246
	s_load_dwordx2 s[4:5], s[0:1], 0xf0
	v_lshlrev_b32_e32 v192, 16, v178
	v_mov_b32_e32 v131, v99
	v_mov_b32_e32 v101, v98
	s_waitcnt lgkmcnt(0)
	v_lshl_add_u64 v[102:103], s[4:5], 0, v[140:141]
	v_lshl_add_u64 v[108:109], v[102:103], 0, v[192:193]
	global_load_dwordx2 v[238:239], v[108:109], off
	v_add_co_u32_e32 v240, vcc, 0x4000, v108
	v_addc_co_u32_e32 v241, vcc, 0, v109, vcc
	global_load_dwordx2 v[240:241], v[240:241], off
	v_add_co_u32_e32 v242, vcc, 0x8000, v108
	v_addc_co_u32_e32 v243, vcc, 0, v109, vcc
	global_load_dwordx2 v[242:243], v[242:243], off
	v_add_co_u32_e32 v244, vcc, 0xc000, v108
	v_addc_co_u32_e32 v245, vcc, 0, v109, vcc
	global_load_dwordx2 v[244:245], v[244:245], off
	v_add_co_u32_e32 v246, vcc, 0x20000, v108
	v_addc_co_u32_e32 v247, vcc, 0, v109, vcc
	global_load_dwordx2 v[246:247], v[246:247], off
	v_add_co_u32_e32 v248, vcc, 0x24000, v108
	v_addc_co_u32_e32 v249, vcc, 0, v109, vcc
	global_load_dwordx2 v[248:249], v[248:249], off
	v_add_co_u32_e32 v250, vcc, 0x2c000, v108
	v_addc_co_u32_e32 v251, vcc, 0, v109, vcc
	global_load_dwordx2 v[250:251], v[250:251], off
	v_add_co_u32_e32 v252, vcc, 0x28000, v108
	v_addc_co_u32_e32 v253, vcc, 0, v109, vcc
	global_load_dwordx2 v[252:253], v[252:253], off
	v_add_co_u32_e32 v110, vcc, 0x4000, v108
	s_waitcnt vmcnt(0)
	v_mov_b32_e32 v102, v238
	v_mov_b32_e32 v103, v239
	s_nop 0
	v_addc_co_u32_e32 v111, vcc, 0, v109, vcc
	v_mov_b32_e32 v110, v240
	v_mov_b32_e32 v111, v241
	s_mov_b32 s4, 0x20000
	s_waitcnt vmcnt(1)
	v_mov_b32_e32 v140, v102
	s_waitcnt vmcnt(0)
	v_mov_b32_e32 v141, v110
	v_mov_b32_e32 v110, v103
	v_pk_mul_f32 v[102:103], v[104:105], v[110:111]
	v_pk_mul_f32 v[110:111], v[138:139], v[110:111]
	v_pk_fma_f32 v[102:103], v[138:139], v[140:141], v[102:103] neg_lo:[0,0,1] neg_hi:[0,0,1]
	v_pk_fma_f32 v[104:105], v[104:105], v[140:141], v[110:111]
	v_add_co_u32_e32 v110, vcc, 0x8000, v108
	s_nop 1
	v_addc_co_u32_e32 v111, vcc, 0, v109, vcc
	v_add_co_u32_e32 v138, vcc, 0xc000, v108
	v_mov_b32_e32 v110, v242
	v_mov_b32_e32 v111, v243
	s_nop 0
	v_addc_co_u32_e32 v139, vcc, 0, v109, vcc
	v_mov_b32_e32 v138, v244
	v_mov_b32_e32 v139, v245
	s_waitcnt vmcnt(1)
	v_mov_b32_e32 v140, v110
	s_waitcnt vmcnt(0)
	v_mov_b32_e32 v141, v138
	v_mov_b32_e32 v138, v111
	v_pk_mul_f32 v[110:111], v[106:107], v[138:139]
	s_nop 0
	v_pk_fma_f32 v[110:111], v[134:135], v[140:141], v[110:111] neg_lo:[0,0,1] neg_hi:[0,0,1]
	v_pk_mul_f32 v[134:135], v[134:135], v[138:139]
	s_nop 0
	v_pk_fma_f32 v[106:107], v[106:107], v[140:141], v[134:135]
	v_add_co_u32_e32 v134, vcc, s4, v108
	s_mov_b32 s4, 0x24000
	s_nop 0
	v_addc_co_u32_e32 v135, vcc, 0, v109, vcc
	v_add_co_u32_e32 v138, vcc, s4, v108
	v_mov_b32_e32 v134, v246
	v_mov_b32_e32 v135, v247
	s_nop 0
	v_addc_co_u32_e32 v139, vcc, 0, v109, vcc
	v_mov_b32_e32 v138, v248
	v_mov_b32_e32 v139, v249
	s_mov_b32 s4, 0x2c000
	s_waitcnt vmcnt(1)
	v_mov_b32_e32 v140, v134
	s_waitcnt vmcnt(0)
	v_mov_b32_e32 v141, v138
	v_mov_b32_e32 v138, v135
	v_pk_mul_f32 v[134:135], v[96:97], v[138:139]
	s_nop 0
	v_pk_fma_f32 v[134:135], v[132:133], v[140:141], v[134:135] neg_lo:[0,0,1] neg_hi:[0,0,1]
	v_pk_mul_f32 v[132:133], v[132:133], v[138:139]
	s_nop 0
	v_pk_fma_f32 v[96:97], v[96:97], v[140:141], v[132:133]
	v_add_co_u32_e32 v132, vcc, s4, v108
	s_mov_b32 s4, 0x28000
	s_nop 0
	v_addc_co_u32_e32 v133, vcc, 0, v109, vcc
	v_add_co_u32_e32 v108, vcc, s4, v108
	v_mov_b32_e32 v132, v250
	v_mov_b32_e32 v133, v251
	s_nop 0
	v_addc_co_u32_e32 v109, vcc, 0, v109, vcc
	v_mov_b32_e32 v108, v252
	v_mov_b32_e32 v109, v253
	s_waitcnt vmcnt(1)
	v_mov_b32_e32 v141, v133
	v_pk_mul_f32 v[98:99], v[98:99], v[132:133]
	v_mov_b32_e32 v139, v132
	s_waitcnt vmcnt(0)
	v_mov_b32_e32 v140, v109
	v_mov_b32_e32 v138, v108
	v_pk_mul_f32 v[140:141], v[100:101], v[140:141]
	v_mul_f32_e32 v100, v100, v108
	v_mul_f32_e32 v108, v130, v109
	v_mov_b32_e32 v101, v98
	v_mov_b32_e32 v109, v99
	v_pk_fma_f32 v[138:139], v[130:131], v[138:139], v[140:141] neg_lo:[0,0,1] neg_hi:[0,0,1]
	v_pk_add_f32 v[100:101], v[100:101], v[108:109]
	v_mov_b32_e32 v99, v139
	v_mov_b32_e32 v98, v101
	v_mov_b32_e32 v130, v138
	v_mov_b32_e32 v133, v135
	v_mov_b32_e32 v132, v134
	v_mov_b32_e32 v135, v111
	v_mov_b32_e32 v134, v110
	v_mov_b32_e32 v139, v103
	v_mov_b32_e32 v138, v102

; DI unsigned pk2(float a, float b) { f2_t v = {a, b}; bf2_t r = __builtin_convertvector(v, bf2_t); return __builtin_bit_cast(unsigned, r); }
; DI float xsum32(float x) { const unsigned u = __float_as_uint(x); const auto r2 = __builtin_amdgcn_permlane32_swap(u, u, false, false); return __uint_as_float(r2[0]) + __uint_as_float(r2[1]); }
; DI void epi_inproj(const Params& p, int l, int mtile, int n0, f32x16 (&acc)[2][4], char* smem) {
;     ...
;             for (int i = 0; i < 2; ++i) {
;                 float ss = 0.f;
; #pragma unroll
;                 for (int e = 0; e < 16; ++e) ss += acc[i][j][e] * acc[i][j][e];
;                 ss = xsum32(ss);
;                 const float rstd = rsqrtf(ss * (1.f / 32.f) + EPS) * qs;
; #pragma unroll
;                 for (int q = 0; q < 4; ++q) {
;                     const float4 w4 = *(const float4*)(nwt + 8 * q + 4 * h);
;                     acc[i][j][4 * q + 0] *= rstd * w4.x; acc[i][j][4 * q + 1] *= rstd * w4.y;
;                     acc[i][j][4 * q + 2] *= rstd * w4.z; acc[i][j][4 * q + 3] *= rstd * w4.w;
;                 }
;                 if (rope) {
;                     const float* tab = p.rope32 + (size_t)t * 2;
; #pragma unroll
;                     for (int q = 0; q < 2; ++q) {
; #pragma unroll
;                         for (int e = 0; e < 4; ++e) {
;                             const float2 cs = *(const float2*)(tab + (size_t)(8 * q + 4 * h + e) * (SEQ * 2));
;                             const float x1 = acc[i][j][4 * q + e], x2 = acc[i][j][4 * q + 8 + e];
;                             acc[i][j][4 * q + e] = x1 * cs.x - x2 * cs.y;
;                             acc[i][j][4 * q + 8 + e] = x2 * cs.x + x1 * cs.y;
;                         }
;     ...
; #pragma unroll
;         for (int i = 0; i < 2; ++i)
; #pragma unroll
;             for (int q = 0; q < 4; ++q) {
;                 uint2 o; o.x = pk2(acc[i][j][4 * q], acc[i][j][4 * q + 1]); o.y = pk2(acc[i][j][4 * q + 2], acc[i][j][4 * q + 3]);
;                 stage_quad_bf16(sb, 32 * j + r, 4 * i + q, h, o);
;             }
.LBB0_256:
	v_cvt_pk_bf16_f32 v64, v122, v123
	v_cvt_pk_bf16_f32 v65, v120, v121
	ds_write_b64 v158, v[64:65] offset:4096
	v_cvt_pk_bf16_f32 v64, v124, v125
	v_cvt_pk_bf16_f32 v65, v118, v137
	ds_write_b64 v156, v[64:65] offset:4096
	v_cvt_pk_bf16_f32 v64, v114, v115
	v_cvt_pk_bf16_f32 v65, v116, v117
	ds_write_b64 v152, v[64:65] offset:4096
	v_cvt_pk_bf16_f32 v64, v128, v129
	v_cvt_pk_bf16_f32 v65, v112, v136
	ds_write_b64 v150, v[64:65] offset:4096
	v_cvt_pk_bf16_f32 v64, v138, v139
	v_cvt_pk_bf16_f32 v65, v134, v135
	ds_write_b64 v151, v[64:65] offset:4096
	v_cvt_pk_bf16_f32 v64, v132, v133
	v_cvt_pk_bf16_f32 v65, v130, v99
	ds_write_b64 v153, v[64:65] offset:4096
	v_cvt_pk_bf16_f32 v64, v104, v105
	v_cvt_pk_bf16_f32 v65, v106, v107
	ds_write_b64 v154, v[64:65] offset:4096
	v_cvt_pk_bf16_f32 v64, v96, v97
	v_cvt_pk_bf16_f32 v65, v100, v98
	s_and_b64 vcc, exec, s[42:43]
	s_mov_b64 s[4:5], -1
	ds_write_b64 v155, v[64:65] offset:4096
	s_cbranch_vccnz .LBB0_269
	v_or_b32_e32 v94, 64, v148
	s_and_b64 vcc, exec, s[40:41]
	v_mul_f32_e32 v112, v49, v49
	s_cbranch_vccnz .LBB0_263
	v_fma_f32 v70, v48, v48, v112
	v_fmac_f32_e32 v70, v50, v50
	v_fmac_f32_e32 v70, v51, v51
	v_fmac_f32_e32 v70, v52, v52
	v_fmac_f32_e32 v70, v53, v53
	v_fmac_f32_e32 v70, v54, v54
	v_fmac_f32_e32 v70, v55, v55
	v_fmac_f32_e32 v70, v56, v56
	v_fmac_f32_e32 v70, v57, v57
	v_pk_mul_f32 v[68:69], v[58:59], v[58:59]
	v_pk_mul_f32 v[66:67], v[60:61], v[60:61]
	v_add_f32_e32 v68, v68, v70
	v_add_f32_e32 v68, v69, v68
	v_add_f32_e32 v66, v66, v68
	v_pk_mul_f32 v[64:65], v[62:63], v[62:63]
	v_add_f32_e32 v66, v67, v66
	v_add_f32_e32 v64, v64, v66
	v_add_f32_e32 v64, v65, v64
	v_mov_b32_e32 v65, v64
	s_nop 1
	v_permlane32_swap_b32_e32 v64, v65
	v_add_f32_e32 v64, v64, v65
	v_fmamk_f32 v64, v64, 0x3d000000, v201
	v_cmp_gt_f32_e32 vcc, s87, v64
	v_mul_f32_e32 v65, 0x4b800000, v64
	v_ashrrev_i32_e32 v95, 31, v94
	v_cndmask_b32_e32 v64, v64, v65, vcc
	v_rsq_f32_e32 v64, v64
	v_mov_b32_e32 v100, v63
	v_mov_b32_e32 v101, v55
	v_lshlrev_b64 v[108:109], 3, v[94:95]
	v_mul_f32_e32 v65, 0x45800000, v64
	v_cndmask_b32_e32 v64, v64, v65, vcc
	v_mul_f32_e32 v98, v179, v64
	global_load_dwordx4 v[64:67], v[146:147], off offset:32
	s_andn2_b64 vcc, exec, s[60:61]
	s_waitcnt vmcnt(0)
	v_mul_f32_e32 v68, v66, v98
	v_mul_f32_e32 v86, v54, v68
	global_load_dwordx4 v[72:75], v[146:147], off
	global_load_dwordx4 v[68:71], v[146:147], off offset:64
	v_pk_mul_f32 v[80:81], v[64:65], v[98:99] op_sel_hi:[1,0]
	v_mov_b32_e32 v111, v67
	v_pk_mul_f32 v[92:93], v[52:53], v[80:81]
	v_cndmask_b32_e64 v67, 0, 1, s[60:61]
	v_cmp_ne_u32_e64 s[44:45], 1, v67
	s_waitcnt vmcnt(1)
	v_pk_mul_f32 v[76:77], v[72:73], v[98:99] op_sel_hi:[1,0]
	s_nop 0
	v_pk_mul_f32 v[90:91], v[48:49], v[76:77]
	s_waitcnt vmcnt(0)
	v_pk_mul_f32 v[76:77], v[68:69], v[98:99] op_sel_hi:[1,0]
	s_nop 0
	v_pk_mul_f32 v[82:83], v[56:57], v[76:77]
	v_pk_mul_f32 v[76:77], v[74:75], v[98:99] op_sel_hi:[1,0]
	s_nop 0
	v_pk_mul_f32 v[88:89], v[50:51], v[76:77]
	v_pk_mul_f32 v[76:77], v[98:99], v[70:71] op_sel_hi:[0,1]
	v_pk_mul_f32 v[84:85], v[58:59], v[76:77]
	global_load_dwordx4 v[76:79], v[146:147], off offset:96
	s_waitcnt vmcnt(0)
	v_pk_mul_f32 v[80:81], v[98:99], v[76:77] op_sel_hi:[0,1]
	v_mov_b32_e32 v110, v79
	v_pk_mul_f32 v[96:97], v[60:61], v[80:81]
	v_mul_f32_e32 v80, v98, v78
	v_pk_mul_f32 v[98:99], v[98:99], v[110:111] op_sel_hi:[0,1]
	v_mul_f32_e32 v80, v62, v80
	v_pk_mul_f32 v[104:105], v[100:101], v[98:99]
	s_cbranch_vccnz .LBB0_260
	s_load_dwordx2 s[4:5], s[0:1], 0xf0
	v_lshlrev_b32_e32 v192, 16, v178
	v_mov_b32_e32 v81, v104
	v_mov_b32_e32 v87, v105
	s_waitcnt lgkmcnt(0)
	v_lshl_add_u64 v[98:99], s[4:5], 0, v[108:109]
	v_lshl_add_u64 v[106:107], v[98:99], 0, v[192:193]
	global_load_dwordx2 v[238:239], v[106:107], off
	v_add_co_u32_e32 v240, vcc, 0x4000, v106
	v_addc_co_u32_e32 v241, vcc, 0, v107, vcc
	global_load_dwordx2 v[240:241], v[240:241], off
	v_add_co_u32_e32 v242, vcc, 0x8000, v106
	v_addc_co_u32_e32 v243, vcc, 0, v107, vcc
	global_load_dwordx2 v[242:243], v[242:243], off
	v_add_co_u32_e32 v244, vcc, 0xc000, v106
	v_addc_co_u32_e32 v245, vcc, 0, v107, vcc
	global_load_dwordx2 v[244:245], v[244:245], off
	v_add_co_u32_e32 v246, vcc, 0x20000, v106
	v_addc_co_u32_e32 v247, vcc, 0, v107, vcc
	global_load_dwordx2 v[246:247], v[246:247], off
	v_add_co_u32_e32 v248, vcc, 0x24000, v106
	v_addc_co_u32_e32 v249, vcc, 0, v107, vcc
	global_load_dwordx2 v[248:249], v[248:249], off
	v_add_co_u32_e32 v250, vcc, 0x2c000, v106
	v_addc_co_u32_e32 v251, vcc, 0, v107, vcc
	global_load_dwordx2 v[250:251], v[250:251], off
	v_add_co_u32_e32 v252, vcc, 0x28000, v106
	v_addc_co_u32_e32 v253, vcc, 0, v107, vcc
	global_load_dwordx2 v[252:253], v[252:253], off
	v_add_co_u32_e32 v100, vcc, 0x4000, v106
	s_waitcnt vmcnt(0)
	v_mov_b32_e32 v98, v238
	v_mov_b32_e32 v99, v239
	s_nop 0
	v_addc_co_u32_e32 v101, vcc, 0, v107, vcc
	v_mov_b32_e32 v100, v240
	v_mov_b32_e32 v101, v241
	s_mov_b32 s4, 0x20000
	s_waitcnt vmcnt(1)
	v_mov_b32_e32 v102, v98
	s_waitcnt vmcnt(0)
	v_mov_b32_e32 v103, v100
	v_mov_b32_e32 v100, v99
	v_pk_mul_f32 v[98:99], v[82:83], v[100:101]
	s_nop 0
	v_pk_fma_f32 v[98:99], v[90:91], v[102:103], v[98:99] neg_lo:[0,0,1] neg_hi:[0,0,1]
	v_pk_mul_f32 v[90:91], v[90:91], v[100:101]
	s_nop 0
	v_pk_fma_f32 v[82:83], v[82:83], v[102:103], v[90:91]
	v_add_co_u32_e32 v90, vcc, 0x8000, v106
	s_nop 1
	v_addc_co_u32_e32 v91, vcc, 0, v107, vcc
	v_add_co_u32_e32 v100, vcc, 0xc000, v106
	v_mov_b32_e32 v90, v242
	v_mov_b32_e32 v91, v243
	s_nop 0
	v_addc_co_u32_e32 v101, vcc, 0, v107, vcc
	v_mov_b32_e32 v102, v244
	v_mov_b32_e32 v103, v245
	s_waitcnt vmcnt(1)
; DI void epi_inproj(const Params& p, int l, int mtile, int n0, f32x16 (&acc)[2][4], char* smem) {
;     ...
;                 if (rope) {
;                     const float* tab = p.rope32 + (size_t)t * 2;
; #pragma unroll
;                     for (int q = 0; q < 2; ++q) {
; #pragma unroll
;                         for (int e = 0; e < 4; ++e) {
;                             const float2 cs = *(const float2*)(tab + (size_t)(8 * q + 4 * h + e) * (SEQ * 2));
;                             const float x1 = acc[i][j][4 * q + e], x2 = acc[i][j][4 * q + 8 + e];
;                             acc[i][j][4 * q + e] = x1 * cs.x - x2 * cs.y;
;                             acc[i][j][4 * q + 8 + e] = x2 * cs.x + x1 * cs.y;
;                         }
	v_mov_b32_e32 v114, v90
	s_waitcnt vmcnt(0)
	v_mov_b32_e32 v115, v102
	v_mov_b32_e32 v102, v91
	v_pk_mul_f32 v[90:91], v[84:85], v[102:103]
	s_nop 0
	v_pk_fma_f32 v[100:101], v[88:89], v[114:115], v[90:91] neg_lo:[0,0,1] neg_hi:[0,0,1]
	v_pk_mul_f32 v[88:89], v[88:89], v[102:103]
	s_nop 0
	v_pk_fma_f32 v[84:85], v[84:85], v[114:115], v[88:89]
	v_add_co_u32_e32 v88, vcc, s4, v106
	s_mov_b32 s4, 0x24000
	s_nop 0
	v_addc_co_u32_e32 v89, vcc, 0, v107, vcc
	v_add_co_u32_e32 v90, vcc, s4, v106
	v_mov_b32_e32 v88, v246
	v_mov_b32_e32 v89, v247
	s_nop 0
	v_addc_co_u32_e32 v91, vcc, 0, v107, vcc
	v_mov_b32_e32 v90, v248
	v_mov_b32_e32 v91, v249
	s_mov_b32 s4, 0x2c000
	s_waitcnt vmcnt(1)
	v_mov_b32_e32 v114, v88
	s_waitcnt vmcnt(0)
	v_mov_b32_e32 v115, v90
	v_mov_b32_e32 v90, v89
	v_pk_mul_f32 v[88:89], v[96:97], v[90:91]
	s_nop 0
	v_pk_fma_f32 v[102:103], v[92:93], v[114:115], v[88:89] neg_lo:[0,0,1] neg_hi:[0,0,1]
	v_pk_mul_f32 v[88:89], v[92:93], v[90:91]
	s_nop 0
	v_pk_fma_f32 v[96:97], v[96:97], v[114:115], v[88:89]
	v_add_co_u32_e32 v88, vcc, s4, v106
	s_mov_b32 s4, 0x28000
	s_nop 0
	v_addc_co_u32_e32 v89, vcc, 0, v107, vcc
	v_add_co_u32_e32 v90, vcc, s4, v106
	v_mov_b32_e32 v88, v250
	v_mov_b32_e32 v89, v251
	s_nop 0
	v_addc_co_u32_e32 v91, vcc, 0, v107, vcc
	v_mov_b32_e32 v90, v252
	v_mov_b32_e32 v91, v253
	s_waitcnt vmcnt(1)
	v_mov_b32_e32 v107, v89
	v_mov_b32_e32 v93, v88
	v_pk_mul_f32 v[88:89], v[104:105], v[88:89]
	s_waitcnt vmcnt(0)
	v_mov_b32_e32 v106, v91
	v_mov_b32_e32 v92, v90
	v_pk_mul_f32 v[106:107], v[80:81], v[106:107]
	v_mul_f32_e32 v80, v80, v90
	v_pk_fma_f32 v[106:107], v[86:87], v[92:93], v[106:107] neg_lo:[0,0,1] neg_hi:[0,0,1]
	v_mul_f32_e32 v86, v86, v91
	v_mov_b32_e32 v81, v88
	v_mov_b32_e32 v87, v89
	v_pk_add_f32 v[80:81], v[80:81], v[86:87]
	v_mov_b32_e32 v90, v98
	v_mov_b32_e32 v91, v99
	v_mov_b32_e32 v88, v100
	v_mov_b32_e32 v89, v101
	v_mov_b32_e32 v92, v102
	v_mov_b32_e32 v93, v103
	v_mov_b32_e32 v86, v106
	v_mov_b32_e32 v105, v107
	v_mov_b32_e32 v104, v81
; DI float xsum32(float x) { const unsigned u = __float_as_uint(x); const auto r2 = __builtin_amdgcn_permlane32_swap(u, u, false, false); return __uint_as_float(r2[0]) + __uint_as_float(r2[1]); }
; DI void epi_inproj(const Params& p, int l, int mtile, int n0, f32x16 (&acc)[2][4], char* smem) {
;     ...
;             for (int i = 0; i < 2; ++i) {
;                 float ss = 0.f;
; #pragma unroll
;                 for (int e = 0; e < 16; ++e) ss += acc[i][j][e] * acc[i][j][e];
;                 ss = xsum32(ss);
;                 const float rstd = rsqrtf(ss * (1.f / 32.f) + EPS) * qs;
; #pragma unroll
;                 for (int q = 0; q < 4; ++q) {
;                     const float4 w4 = *(const float4*)(nwt + 8 * q + 4 * h);
;                     acc[i][j][4 * q + 0] *= rstd * w4.x; acc[i][j][4 * q + 1] *= rstd * w4.y;
;                     acc[i][j][4 * q + 2] *= rstd * w4.z; acc[i][j][4 * q + 3] *= rstd * w4.w;
;                 }
;                 if (rope) {
;                     const float* tab = p.rope32 + (size_t)t * 2;
; #pragma unroll
;                     for (int q = 0; q < 2; ++q) {
; #pragma unroll
;                         for (int e = 0; e < 4; ++e) {
;                             const float2 cs = *(const float2*)(tab + (size_t)(8 * q + 4 * h + e) * (SEQ * 2));
;                             const float x1 = acc[i][j][4 * q + e], x2 = acc[i][j][4 * q + 8 + e];
;                             acc[i][j][4 * q + e] = x1 * cs.x - x2 * cs.y;
;                             acc[i][j][4 * q + 8 + e] = x2 * cs.x + x1 * cs.y;
;                         }
.LBB0_260:
	v_mul_f32_e32 v67, v33, v33
	v_fmac_f32_e32 v67, v32, v32
	v_fmac_f32_e32 v67, v34, v34
	v_fmac_f32_e32 v67, v35, v35
	v_fmac_f32_e32 v67, v36, v36
	v_fmac_f32_e32 v67, v37, v37
	v_fmac_f32_e32 v67, v38, v38
	v_fmac_f32_e32 v67, v39, v39
	v_fmac_f32_e32 v67, v40, v40
	v_fmac_f32_e32 v67, v41, v41
	v_pk_mul_f32 v[102:103], v[42:43], v[42:43]
	v_pk_mul_f32 v[100:101], v[44:45], v[44:45]
	v_add_f32_e32 v67, v102, v67
	v_add_f32_e32 v67, v103, v67
	v_add_f32_e32 v67, v100, v67
	v_pk_mul_f32 v[98:99], v[46:47], v[46:47]
	v_add_f32_e32 v67, v101, v67
	v_add_f32_e32 v67, v98, v67
	v_add_f32_e32 v67, v99, v67
	v_mov_b32_e32 v79, v67
	s_nop 1
	v_permlane32_swap_b32_e32 v67, v79
	v_add_f32_e32 v67, v67, v79
	v_fmamk_f32 v67, v67, 0x3d000000, v201
	v_mul_f32_e32 v79, 0x4b800000, v67
	v_cmp_gt_f32_e32 vcc, s87, v67
	s_nop 1
	v_cndmask_b32_e32 v67, v67, v79, vcc
	v_rsq_f32_e32 v67, v67
	s_nop 0
	v_mul_f32_e32 v79, 0x45800000, v67
	v_cndmask_b32_e32 v67, v67, v79, vcc
	v_mul_f32_e32 v114, v179, v67
	v_mul_f32_e32 v66, v66, v114
	v_mul_f32_e32 v98, v38, v66
	v_pk_mul_f32 v[66:67], v[72:73], v[114:115] op_sel_hi:[1,0]
	v_pk_mul_f32 v[64:65], v[64:65], v[114:115] op_sel_hi:[1,0]
	v_pk_mul_f32 v[106:107], v[32:33], v[66:67]
	v_pk_mul_f32 v[66:67], v[68:69], v[114:115] op_sel_hi:[1,0]
	v_pk_mul_f32 v[100:101], v[36:37], v[64:65]
	v_pk_mul_f32 v[72:73], v[40:41], v[66:67]
	v_pk_mul_f32 v[66:67], v[74:75], v[114:115] op_sel_hi:[1,0]
	v_pk_mul_f32 v[64:65], v[76:77], v[114:115] op_sel_hi:[1,0]
	v_pk_mul_f32 v[102:103], v[34:35], v[66:67]
	v_pk_mul_f32 v[66:67], v[70:71], v[114:115] op_sel_hi:[1,0]
	v_mov_b32_e32 v70, v47
	v_pk_mul_f32 v[74:75], v[42:43], v[66:67]
	v_mul_f32_e32 v66, v78, v114
	v_mul_f32_e32 v68, v46, v66
	v_pk_mul_f32 v[66:67], v[110:111], v[114:115] op_sel_hi:[1,0]
	v_mov_b32_e32 v71, v39
	v_pk_mul_f32 v[64:65], v[44:45], v[64:65]
	s_and_b64 vcc, exec, s[44:45]
	v_pk_mul_f32 v[66:67], v[70:71], v[66:67]
	s_cbranch_vccnz .LBB0_262
	s_load_dwordx2 s[4:5], s[0:1], 0xf0
	v_lshlrev_b32_e32 v192, 16, v178
	v_mov_b32_e32 v99, v67
	v_mov_b32_e32 v69, v66
	s_waitcnt lgkmcnt(0)
	v_lshl_add_u64 v[70:71], s[4:5], 0, v[108:109]
	v_lshl_add_u64 v[76:77], v[70:71], 0, v[192:193]
	global_load_dwordx2 v[238:239], v[76:77], off
	v_add_co_u32_e32 v240, vcc, 0x4000, v76
	v_addc_co_u32_e32 v241, vcc, 0, v77, vcc
	global_load_dwordx2 v[240:241], v[240:241], off
	v_add_co_u32_e32 v242, vcc, 0x8000, v76
	v_addc_co_u32_e32 v243, vcc, 0, v77, vcc
	global_load_dwordx2 v[242:243], v[242:243], off
	v_add_co_u32_e32 v244, vcc, 0xc000, v76
	v_addc_co_u32_e32 v245, vcc, 0, v77, vcc
	global_load_dwordx2 v[244:245], v[244:245], off
	v_add_co_u32_e32 v246, vcc, 0x20000, v76
	v_addc_co_u32_e32 v247, vcc, 0, v77, vcc
	global_load_dwordx2 v[246:247], v[246:247], off
	v_add_co_u32_e32 v248, vcc, 0x24000, v76
	v_addc_co_u32_e32 v249, vcc, 0, v77, vcc
	global_load_dwordx2 v[248:249], v[248:249], off
	v_add_co_u32_e32 v250, vcc, 0x2c000, v76
	v_addc_co_u32_e32 v251, vcc, 0, v77, vcc
	global_load_dwordx2 v[250:251], v[250:251], off
	v_add_co_u32_e32 v252, vcc, 0x28000, v76
	v_addc_co_u32_e32 v253, vcc, 0, v77, vcc
	global_load_dwordx2 v[252:253], v[252:253], off
	v_add_co_u32_e32 v78, vcc, 0x4000, v76
	s_waitcnt vmcnt(0)
	v_mov_b32_e32 v70, v238
	v_mov_b32_e32 v71, v239
	s_nop 0
	v_addc_co_u32_e32 v79, vcc, 0, v77, vcc
	v_mov_b32_e32 v78, v240
	v_mov_b32_e32 v79, v241
	s_mov_b32 s4, 0x20000
	s_waitcnt vmcnt(1)
	v_mov_b32_e32 v108, v70
	s_waitcnt vmcnt(0)
	v_mov_b32_e32 v109, v78
	v_mov_b32_e32 v78, v71
	v_pk_mul_f32 v[70:71], v[72:73], v[78:79]
	v_pk_mul_f32 v[78:79], v[106:107], v[78:79]
	v_pk_fma_f32 v[70:71], v[106:107], v[108:109], v[70:71] neg_lo:[0,0,1] neg_hi:[0,0,1]
	v_pk_fma_f32 v[72:73], v[72:73], v[108:109], v[78:79]
	v_add_co_u32_e32 v78, vcc, 0x8000, v76
	s_nop 1
	v_addc_co_u32_e32 v79, vcc, 0, v77, vcc
	v_add_co_u32_e32 v106, vcc, 0xc000, v76
	v_mov_b32_e32 v78, v242
	v_mov_b32_e32 v79, v243
	s_nop 0
	v_addc_co_u32_e32 v107, vcc, 0, v77, vcc
	v_mov_b32_e32 v106, v244
	v_mov_b32_e32 v107, v245
	s_waitcnt vmcnt(1)
	v_mov_b32_e32 v108, v78
	s_waitcnt vmcnt(0)
	v_mov_b32_e32 v109, v106
	v_mov_b32_e32 v106, v79
	v_pk_mul_f32 v[78:79], v[74:75], v[106:107]
	s_nop 0
	v_pk_fma_f32 v[78:79], v[102:103], v[108:109], v[78:79] neg_lo:[0,0,1] neg_hi:[0,0,1]
	v_pk_mul_f32 v[102:103], v[102:103], v[106:107]
	s_nop 0
	v_pk_fma_f32 v[74:75], v[74:75], v[108:109], v[102:103]
	v_add_co_u32_e32 v102, vcc, s4, v76
	s_mov_b32 s4, 0x24000
	s_nop 0
	v_addc_co_u32_e32 v103, vcc, 0, v77, vcc
	v_add_co_u32_e32 v106, vcc, s4, v76
	v_mov_b32_e32 v102, v246
	v_mov_b32_e32 v103, v247
	s_nop 0
	v_addc_co_u32_e32 v107, vcc, 0, v77, vcc
	v_mov_b32_e32 v106, v248
	v_mov_b32_e32 v107, v249
	s_mov_b32 s4, 0x2c000
	s_waitcnt vmcnt(1)
	v_mov_b32_e32 v108, v102
	s_waitcnt vmcnt(0)
	v_mov_b32_e32 v109, v106
	v_mov_b32_e32 v106, v103
	v_pk_mul_f32 v[102:103], v[64:65], v[106:107]
	s_nop 0
	v_pk_fma_f32 v[102:103], v[100:101], v[108:109], v[102:103] neg_lo:[0,0,1] neg_hi:[0,0,1]
	v_pk_mul_f32 v[100:101], v[100:101], v[106:107]
	s_nop 0
	v_pk_fma_f32 v[64:65], v[64:65], v[108:109], v[100:101]
	v_add_co_u32_e32 v100, vcc, s4, v76
	s_mov_b32 s4, 0x28000
	s_nop 0
	v_addc_co_u32_e32 v101, vcc, 0, v77, vcc
	v_add_co_u32_e32 v76, vcc, s4, v76
	v_mov_b32_e32 v100, v250
	v_mov_b32_e32 v101, v251
	s_nop 0
	v_addc_co_u32_e32 v77, vcc, 0, v77, vcc
	v_mov_b32_e32 v76, v252
	v_mov_b32_e32 v77, v253
	s_waitcnt vmcnt(1)
	v_mov_b32_e32 v109, v101
	v_pk_mul_f32 v[66:67], v[66:67], v[100:101]
	v_mov_b32_e32 v107, v100
	s_waitcnt vmcnt(0)
	v_mov_b32_e32 v108, v77
	v_mov_b32_e32 v106, v76
	v_pk_mul_f32 v[108:109], v[68:69], v[108:109]
	v_mul_f32_e32 v68, v68, v76
	v_mul_f32_e32 v76, v98, v77
	v_mov_b32_e32 v69, v66
	v_mov_b32_e32 v77, v67
	v_pk_fma_f32 v[106:107], v[98:99], v[106:107], v[108:109] neg_lo:[0,0,1] neg_hi:[0,0,1]
	v_pk_add_f32 v[68:69], v[68:69], v[76:77]
	v_mov_b32_e32 v67, v107
	v_mov_b32_e32 v66, v69
	v_mov_b32_e32 v98, v106
	v_mov_b32_e32 v101, v103
	v_mov_b32_e32 v100, v102
	v_mov_b32_e32 v103, v79
	v_mov_b32_e32 v102, v78
	v_mov_b32_e32 v107, v71
	v_mov_b32_e32 v106, v70

; DI unsigned pk2(float a, float b) { f2_t v = {a, b}; bf2_t r = __builtin_convertvector(v, bf2_t); return __builtin_bit_cast(unsigned, r); }
; DI float xsum32(float x) { const unsigned u = __float_as_uint(x); const auto r2 = __builtin_amdgcn_permlane32_swap(u, u, false, false); return __uint_as_float(r2[0]) + __uint_as_float(r2[1]); }
; DI void epi_inproj(const Params& p, int l, int mtile, int n0, f32x16 (&acc)[2][4], char* smem) {
;     ...
;             for (int i = 0; i < 2; ++i) {
;                 float ss = 0.f;
; #pragma unroll
;                 for (int e = 0; e < 16; ++e) ss += acc[i][j][e] * acc[i][j][e];
;                 ss = xsum32(ss);
;                 const float rstd = rsqrtf(ss * (1.f / 32.f) + EPS) * qs;
; #pragma unroll
;                 for (int q = 0; q < 4; ++q) {
;                     const float4 w4 = *(const float4*)(nwt + 8 * q + 4 * h);
;                     acc[i][j][4 * q + 0] *= rstd * w4.x; acc[i][j][4 * q + 1] *= rstd * w4.y;
;                     acc[i][j][4 * q + 2] *= rstd * w4.z; acc[i][j][4 * q + 3] *= rstd * w4.w;
;                 }
;                 if (rope) {
;                     const float* tab = p.rope32 + (size_t)t * 2;
; #pragma unroll
;                     for (int q = 0; q < 2; ++q) {
; #pragma unroll
;                         for (int e = 0; e < 4; ++e) {
;                             const float2 cs = *(const float2*)(tab + (size_t)(8 * q + 4 * h + e) * (SEQ * 2));
;                             const float x1 = acc[i][j][4 * q + e], x2 = acc[i][j][4 * q + 8 + e];
;                             acc[i][j][4 * q + e] = x1 * cs.x - x2 * cs.y;
;                             acc[i][j][4 * q + 8 + e] = x2 * cs.x + x1 * cs.y;
;                         }
;     ...
; #pragma unroll
;         for (int i = 0; i < 2; ++i)
; #pragma unroll
;             for (int q = 0; q < 4; ++q) {
;                 uint2 o; o.x = pk2(acc[i][j][4 * q], acc[i][j][4 * q + 1]); o.y = pk2(acc[i][j][4 * q + 2], acc[i][j][4 * q + 3]);
;                 stage_quad_bf16(sb, 32 * j + r, 4 * i + q, h, o);
;             }
.LBB0_271:
	v_cvt_pk_bf16_f32 v32, v90, v91
	v_cvt_pk_bf16_f32 v33, v88, v89
	ds_write_b64 v158, v[32:33] offset:8192
	v_cvt_pk_bf16_f32 v32, v92, v93
	v_cvt_pk_bf16_f32 v33, v86, v105
	ds_write_b64 v156, v[32:33] offset:8192
	v_cvt_pk_bf16_f32 v32, v82, v83
	v_cvt_pk_bf16_f32 v33, v84, v85
	ds_write_b64 v152, v[32:33] offset:8192
	v_cvt_pk_bf16_f32 v32, v96, v97
	v_cvt_pk_bf16_f32 v33, v80, v104
	ds_write_b64 v150, v[32:33] offset:8192
	v_cvt_pk_bf16_f32 v32, v106, v107
	v_cvt_pk_bf16_f32 v33, v102, v103
	ds_write_b64 v151, v[32:33] offset:8192
	v_cvt_pk_bf16_f32 v32, v100, v101
	v_cvt_pk_bf16_f32 v33, v98, v67
	ds_write_b64 v153, v[32:33] offset:8192
	v_cvt_pk_bf16_f32 v32, v72, v73
	v_cvt_pk_bf16_f32 v33, v74, v75
	ds_write_b64 v154, v[32:33] offset:8192
	v_cvt_pk_bf16_f32 v32, v64, v65
	v_cvt_pk_bf16_f32 v33, v68, v66
	s_and_b64 vcc, exec, s[42:43]
	s_mov_b64 s[4:5], -1
	ds_write_b64 v155, v[32:33] offset:8192
	s_cbranch_vccnz .LBB0_284
	v_cndmask_b32_e64 v32, 0, 1, s[60:61]
	v_or_b32_e32 v64, 0x60, v148
	s_and_b64 vcc, exec, s[40:41]
	v_mul_f32_e32 v80, v17, v17
	v_cmp_ne_u32_e64 s[40:41], 1, v32
	s_cbranch_vccnz .LBB0_278
	global_load_dwordx4 v[32:35], v[146:147], off offset:32
	global_load_dwordx4 v[40:43], v[146:147], off
	global_load_dwordx4 v[36:39], v[146:147], off offset:64
	global_load_dwordx4 v[44:47], v[146:147], off offset:96
	v_fma_f32 v54, v16, v16, v80
	v_fmac_f32_e32 v54, v18, v18
	v_fmac_f32_e32 v54, v19, v19
	v_fmac_f32_e32 v54, v20, v20
	v_fmac_f32_e32 v54, v21, v21
	v_fmac_f32_e32 v54, v22, v22
	v_fmac_f32_e32 v54, v23, v23
	v_fmac_f32_e32 v54, v24, v24
	v_pk_mul_f32 v[52:53], v[26:27], v[26:27]
	v_fmac_f32_e32 v54, v25, v25
	v_add_f32_e32 v52, v52, v54
	v_pk_mul_f32 v[50:51], v[28:29], v[28:29]
	v_add_f32_e32 v52, v53, v52
	v_add_f32_e32 v50, v50, v52
	v_pk_mul_f32 v[48:49], v[30:31], v[30:31]
	v_add_f32_e32 v50, v51, v50
	v_add_f32_e32 v48, v48, v50
	v_add_f32_e32 v48, v49, v48
	v_mov_b32_e32 v49, v48
	s_nop 1
	v_permlane32_swap_b32_e32 v48, v49
	v_add_f32_e32 v48, v48, v49
	v_fmamk_f32 v48, v48, 0x3d000000, v201
	v_mul_f32_e32 v49, 0x4b800000, v48
	v_cmp_gt_f32_e32 vcc, s87, v48
	v_ashrrev_i32_e32 v65, 31, v64
	v_mov_b32_e32 v66, v31
	v_cndmask_b32_e32 v48, v48, v49, vcc
	v_rsq_f32_e32 v48, v48
	v_mov_b32_e32 v67, v23
	v_lshlrev_b64 v[76:77], 3, v[64:65]
	v_mul_f32_e32 v49, 0x45800000, v48
	v_cndmask_b32_e32 v48, v48, v49, vcc
	v_mul_f32_e32 v68, v179, v48
	s_and_b64 vcc, exec, s[40:41]
	s_waitcnt vmcnt(3)
	v_mov_b32_e32 v79, v35
	v_mul_f32_e32 v54, v34, v68
	s_waitcnt vmcnt(2)
	v_pk_mul_f32 v[48:49], v[40:41], v[68:69] op_sel_hi:[1,0]
	s_waitcnt vmcnt(0)
	v_mov_b32_e32 v78, v47
	v_pk_mul_f32 v[50:51], v[36:37], v[68:69] op_sel_hi:[1,0]
	v_pk_mul_f32 v[52:53], v[42:43], v[68:69] op_sel_hi:[1,0]
	v_pk_mul_f32 v[58:59], v[68:69], v[38:39] op_sel_hi:[0,1]
	v_pk_mul_f32 v[62:63], v[32:33], v[68:69] op_sel_hi:[1,0]
	v_pk_mul_f32 v[70:71], v[68:69], v[44:45] op_sel_hi:[0,1]
	v_mul_f32_e32 v55, v68, v46
	v_pk_mul_f32 v[68:69], v[68:69], v[78:79] op_sel_hi:[0,1]
	v_mul_f32_e32 v54, v22, v54
	v_pk_mul_f32 v[60:61], v[16:17], v[48:49]
	v_pk_mul_f32 v[50:51], v[24:25], v[50:51]
	v_pk_mul_f32 v[56:57], v[18:19], v[52:53]
	v_pk_mul_f32 v[52:53], v[26:27], v[58:59]
	v_pk_mul_f32 v[58:59], v[20:21], v[62:63]
	v_pk_mul_f32 v[62:63], v[28:29], v[70:71]
	v_mul_f32_e32 v48, v30, v55
	v_pk_mul_f32 v[74:75], v[66:67], v[68:69]
	s_cbranch_vccnz .LBB0_275
	s_load_dwordx2 s[4:5], s[0:1], 0xf0
	v_lshlrev_b32_e32 v192, 16, v178
	v_mov_b32_e32 v49, v74
	v_mov_b32_e32 v55, v75
	s_waitcnt lgkmcnt(0)
	v_lshl_add_u64 v[66:67], s[4:5], 0, v[76:77]
	v_lshl_add_u64 v[72:73], v[66:67], 0, v[192:193]
	global_load_dwordx2 v[238:239], v[72:73], off
	v_add_co_u32_e32 v240, vcc, 0x4000, v72
	v_addc_co_u32_e32 v241, vcc, 0, v73, vcc
	global_load_dwordx2 v[240:241], v[240:241], off
	v_add_co_u32_e32 v242, vcc, 0x8000, v72
	v_addc_co_u32_e32 v243, vcc, 0, v73, vcc
	global_load_dwordx2 v[242:243], v[242:243], off
	v_add_co_u32_e32 v244, vcc, 0xc000, v72
	v_addc_co_u32_e32 v245, vcc, 0, v73, vcc
	global_load_dwordx2 v[244:245], v[244:245], off
	v_add_co_u32_e32 v246, vcc, 0x20000, v72
	v_addc_co_u32_e32 v247, vcc, 0, v73, vcc
	global_load_dwordx2 v[246:247], v[246:247], off
	v_add_co_u32_e32 v248, vcc, 0x24000, v72
	v_addc_co_u32_e32 v249, vcc, 0, v73, vcc
	global_load_dwordx2 v[248:249], v[248:249], off
	v_add_co_u32_e32 v250, vcc, 0x2c000, v72
	v_addc_co_u32_e32 v251, vcc, 0, v73, vcc
	global_load_dwordx2 v[250:251], v[250:251], off
	v_add_co_u32_e32 v252, vcc, 0x28000, v72
	v_addc_co_u32_e32 v253, vcc, 0, v73, vcc
	global_load_dwordx2 v[252:253], v[252:253], off
	v_add_co_u32_e32 v68, vcc, 0x4000, v72
	s_waitcnt vmcnt(0)
	v_mov_b32_e32 v66, v238
	v_mov_b32_e32 v67, v239
	s_nop 0
	v_addc_co_u32_e32 v69, vcc, 0, v73, vcc
	v_mov_b32_e32 v68, v240
	v_mov_b32_e32 v69, v241
	s_mov_b32 s4, 0x20000
	s_waitcnt vmcnt(1)
	v_mov_b32_e32 v70, v66
	s_waitcnt vmcnt(0)
	v_mov_b32_e32 v71, v68
	v_mov_b32_e32 v68, v67
	v_pk_mul_f32 v[66:67], v[50:51], v[68:69]
	s_nop 0
	v_pk_fma_f32 v[66:67], v[60:61], v[70:71], v[66:67] neg_lo:[0,0,1] neg_hi:[0,0,1]
	v_pk_mul_f32 v[60:61], v[60:61], v[68:69]
	s_nop 0
	v_pk_fma_f32 v[50:51], v[50:51], v[70:71], v[60:61]
	v_add_co_u32_e32 v60, vcc, 0x8000, v72
	s_nop 1
	v_addc_co_u32_e32 v61, vcc, 0, v73, vcc
	v_add_co_u32_e32 v68, vcc, 0xc000, v72
	v_mov_b32_e32 v60, v242
	v_mov_b32_e32 v61, v243
	s_nop 0
	v_addc_co_u32_e32 v69, vcc, 0, v73, vcc
	v_mov_b32_e32 v70, v244
	v_mov_b32_e32 v71, v245
	s_waitcnt vmcnt(1)
	v_mov_b32_e32 v82, v60
	s_waitcnt vmcnt(0)
; DI void epi_inproj(const Params& p, int l, int mtile, int n0, f32x16 (&acc)[2][4], char* smem) {
;     ...
;                 if (rope) {
;                     const float* tab = p.rope32 + (size_t)t * 2;
; #pragma unroll
;                     for (int q = 0; q < 2; ++q) {
; #pragma unroll
;                         for (int e = 0; e < 4; ++e) {
;                             const float2 cs = *(const float2*)(tab + (size_t)(8 * q + 4 * h + e) * (SEQ * 2));
;                             const float x1 = acc[i][j][4 * q + e], x2 = acc[i][j][4 * q + 8 + e];
;                             acc[i][j][4 * q + e] = x1 * cs.x - x2 * cs.y;
;                             acc[i][j][4 * q + 8 + e] = x2 * cs.x + x1 * cs.y;
;                         }
	v_mov_b32_e32 v83, v70
	v_mov_b32_e32 v70, v61
	v_pk_mul_f32 v[60:61], v[52:53], v[70:71]
	s_nop 0
	v_pk_fma_f32 v[68:69], v[56:57], v[82:83], v[60:61] neg_lo:[0,0,1] neg_hi:[0,0,1]
	v_pk_mul_f32 v[56:57], v[56:57], v[70:71]
	s_nop 0
	v_pk_fma_f32 v[52:53], v[52:53], v[82:83], v[56:57]
	v_add_co_u32_e32 v56, vcc, s4, v72
	s_mov_b32 s4, 0x24000
	s_nop 0
	v_addc_co_u32_e32 v57, vcc, 0, v73, vcc
	v_add_co_u32_e32 v60, vcc, s4, v72
	v_mov_b32_e32 v56, v246
	v_mov_b32_e32 v57, v247
	s_nop 0
	v_addc_co_u32_e32 v61, vcc, 0, v73, vcc
	v_mov_b32_e32 v60, v248
	v_mov_b32_e32 v61, v249
	s_mov_b32 s4, 0x2c000
	s_waitcnt vmcnt(1)
	v_mov_b32_e32 v82, v56
	s_waitcnt vmcnt(0)
	v_mov_b32_e32 v83, v60
	v_mov_b32_e32 v60, v57
	v_pk_mul_f32 v[56:57], v[62:63], v[60:61]
	s_nop 0
	v_pk_fma_f32 v[70:71], v[58:59], v[82:83], v[56:57] neg_lo:[0,0,1] neg_hi:[0,0,1]
	v_pk_mul_f32 v[56:57], v[58:59], v[60:61]
	s_nop 0
	v_pk_fma_f32 v[62:63], v[62:63], v[82:83], v[56:57]
	v_add_co_u32_e32 v56, vcc, s4, v72
	s_mov_b32 s4, 0x28000
	s_nop 0
	v_addc_co_u32_e32 v57, vcc, 0, v73, vcc
	v_add_co_u32_e32 v58, vcc, s4, v72
	v_mov_b32_e32 v56, v250
	v_mov_b32_e32 v57, v251
	s_nop 0
	v_addc_co_u32_e32 v59, vcc, 0, v73, vcc
	v_mov_b32_e32 v58, v252
	v_mov_b32_e32 v59, v253
	s_waitcnt vmcnt(1)
	v_mov_b32_e32 v73, v57
	v_mov_b32_e32 v61, v56
	v_pk_mul_f32 v[56:57], v[74:75], v[56:57]
	s_waitcnt vmcnt(0)
	v_mov_b32_e32 v72, v59
	v_mov_b32_e32 v60, v58
	v_pk_mul_f32 v[72:73], v[48:49], v[72:73]
	v_mul_f32_e32 v48, v48, v58
	v_pk_fma_f32 v[72:73], v[54:55], v[60:61], v[72:73] neg_lo:[0,0,1] neg_hi:[0,0,1]
	v_mul_f32_e32 v54, v54, v59
	v_mov_b32_e32 v49, v56
	v_mov_b32_e32 v55, v57
	v_pk_add_f32 v[48:49], v[48:49], v[54:55]
	v_mov_b32_e32 v60, v66
	v_mov_b32_e32 v61, v67
	v_mov_b32_e32 v56, v68
	v_mov_b32_e32 v57, v69
	v_mov_b32_e32 v58, v70
	v_mov_b32_e32 v59, v71
	v_mov_b32_e32 v54, v72
	v_mov_b32_e32 v75, v73
	v_mov_b32_e32 v74, v49
; DI float xsum32(float x) { const unsigned u = __float_as_uint(x); const auto r2 = __builtin_amdgcn_permlane32_swap(u, u, false, false); return __uint_as_float(r2[0]) + __uint_as_float(r2[1]); }
; DI void epi_inproj(const Params& p, int l, int mtile, int n0, f32x16 (&acc)[2][4], char* smem) {
;     ...
;             for (int i = 0; i < 2; ++i) {
;                 float ss = 0.f;
; #pragma unroll
;                 for (int e = 0; e < 16; ++e) ss += acc[i][j][e] * acc[i][j][e];
;                 ss = xsum32(ss);
;                 const float rstd = rsqrtf(ss * (1.f / 32.f) + EPS) * qs;
; #pragma unroll
;                 for (int q = 0; q < 4; ++q) {
;                     const float4 w4 = *(const float4*)(nwt + 8 * q + 4 * h);
;                     acc[i][j][4 * q + 0] *= rstd * w4.x; acc[i][j][4 * q + 1] *= rstd * w4.y;
;                     acc[i][j][4 * q + 2] *= rstd * w4.z; acc[i][j][4 * q + 3] *= rstd * w4.w;
;                 }
;                 if (rope) {
;                     const float* tab = p.rope32 + (size_t)t * 2;
; #pragma unroll
;                     for (int q = 0; q < 2; ++q) {
; #pragma unroll
;                         for (int e = 0; e < 4; ++e) {
;                             const float2 cs = *(const float2*)(tab + (size_t)(8 * q + 4 * h + e) * (SEQ * 2));
;                             const float x1 = acc[i][j][4 * q + e], x2 = acc[i][j][4 * q + 8 + e];
;                             acc[i][j][4 * q + e] = x1 * cs.x - x2 * cs.y;
;                             acc[i][j][4 * q + 8 + e] = x2 * cs.x + x1 * cs.y;
;                         }
.LBB0_275:
	v_mul_f32_e32 v35, v1, v1
	v_fmac_f32_e32 v35, v0, v0
	v_fmac_f32_e32 v35, v2, v2
	v_fmac_f32_e32 v35, v3, v3
	v_fmac_f32_e32 v35, v4, v4
	v_fmac_f32_e32 v35, v5, v5
	v_fmac_f32_e32 v35, v6, v6
	v_fmac_f32_e32 v35, v7, v7
	v_fmac_f32_e32 v35, v8, v8
	v_fmac_f32_e32 v35, v9, v9
	v_pk_mul_f32 v[70:71], v[10:11], v[10:11]
	v_pk_mul_f32 v[68:69], v[12:13], v[12:13]
	v_add_f32_e32 v35, v70, v35
	v_add_f32_e32 v35, v71, v35
	v_add_f32_e32 v35, v68, v35
	v_pk_mul_f32 v[66:67], v[14:15], v[14:15]
	v_add_f32_e32 v35, v69, v35
	v_add_f32_e32 v35, v66, v35
	v_add_f32_e32 v35, v67, v35
	v_mov_b32_e32 v47, v35
	s_nop 1
	v_permlane32_swap_b32_e32 v35, v47
	v_add_f32_e32 v35, v35, v47
	v_fmamk_f32 v35, v35, 0x3d000000, v201
	v_mul_f32_e32 v47, 0x4b800000, v35
	v_cmp_gt_f32_e32 vcc, s87, v35
	s_nop 1
	v_cndmask_b32_e32 v35, v35, v47, vcc
	v_rsq_f32_e32 v35, v35
	s_nop 0
	v_mul_f32_e32 v47, 0x45800000, v35
	v_cndmask_b32_e32 v35, v35, v47, vcc
	v_mul_f32_e32 v82, v179, v35
	v_mul_f32_e32 v34, v34, v82
	v_mul_f32_e32 v66, v6, v34
	v_pk_mul_f32 v[34:35], v[40:41], v[82:83] op_sel_hi:[1,0]
	v_pk_mul_f32 v[32:33], v[32:33], v[82:83] op_sel_hi:[1,0]
	v_pk_mul_f32 v[72:73], v[0:1], v[34:35]
	v_pk_mul_f32 v[34:35], v[36:37], v[82:83] op_sel_hi:[1,0]
	v_pk_mul_f32 v[68:69], v[4:5], v[32:33]
	v_pk_mul_f32 v[40:41], v[8:9], v[34:35]
	v_pk_mul_f32 v[34:35], v[42:43], v[82:83] op_sel_hi:[1,0]
	v_pk_mul_f32 v[32:33], v[44:45], v[82:83] op_sel_hi:[1,0]
	v_pk_mul_f32 v[70:71], v[2:3], v[34:35]
	v_pk_mul_f32 v[34:35], v[38:39], v[82:83] op_sel_hi:[1,0]
	v_mov_b32_e32 v38, v15
	v_pk_mul_f32 v[42:43], v[10:11], v[34:35]
	v_mul_f32_e32 v34, v46, v82
	v_mul_f32_e32 v36, v14, v34
	v_pk_mul_f32 v[34:35], v[78:79], v[82:83] op_sel_hi:[1,0]
	v_mov_b32_e32 v39, v7
	v_pk_mul_f32 v[32:33], v[12:13], v[32:33]
	s_and_b64 vcc, exec, s[40:41]
	v_pk_mul_f32 v[34:35], v[38:39], v[34:35]
	s_cbranch_vccnz .LBB0_277
	s_load_dwordx2 s[4:5], s[0:1], 0xf0
	v_lshlrev_b32_e32 v192, 16, v178
	v_mov_b32_e32 v67, v35
	v_mov_b32_e32 v37, v34
	s_waitcnt lgkmcnt(0)
	v_lshl_add_u64 v[38:39], s[4:5], 0, v[76:77]
	v_lshl_add_u64 v[44:45], v[38:39], 0, v[192:193]
	global_load_dwordx2 v[238:239], v[44:45], off
	v_add_co_u32_e32 v240, vcc, 0x4000, v44
	v_addc_co_u32_e32 v241, vcc, 0, v45, vcc
	global_load_dwordx2 v[240:241], v[240:241], off
	v_add_co_u32_e32 v242, vcc, 0x8000, v44
	v_addc_co_u32_e32 v243, vcc, 0, v45, vcc
	global_load_dwordx2 v[242:243], v[242:243], off
	v_add_co_u32_e32 v244, vcc, 0xc000, v44
	v_addc_co_u32_e32 v245, vcc, 0, v45, vcc
	global_load_dwordx2 v[244:245], v[244:245], off
	v_add_co_u32_e32 v246, vcc, 0x20000, v44
	v_addc_co_u32_e32 v247, vcc, 0, v45, vcc
	global_load_dwordx2 v[246:247], v[246:247], off
	v_add_co_u32_e32 v248, vcc, 0x24000, v44
	v_addc_co_u32_e32 v249, vcc, 0, v45, vcc
	global_load_dwordx2 v[248:249], v[248:249], off
	v_add_co_u32_e32 v250, vcc, 0x2c000, v44
	v_addc_co_u32_e32 v251, vcc, 0, v45, vcc
	global_load_dwordx2 v[250:251], v[250:251], off
	v_add_co_u32_e32 v252, vcc, 0x28000, v44
	v_addc_co_u32_e32 v253, vcc, 0, v45, vcc
	global_load_dwordx2 v[252:253], v[252:253], off
	v_add_co_u32_e32 v46, vcc, 0x4000, v44
	s_waitcnt vmcnt(0)
	v_mov_b32_e32 v38, v238
	v_mov_b32_e32 v39, v239
	s_nop 0
	v_addc_co_u32_e32 v47, vcc, 0, v45, vcc
	v_mov_b32_e32 v46, v240
	v_mov_b32_e32 v47, v241
	s_mov_b32 s4, 0x20000
	s_waitcnt vmcnt(1)
	v_mov_b32_e32 v76, v38
	s_waitcnt vmcnt(0)
	v_mov_b32_e32 v77, v46
	v_mov_b32_e32 v46, v39
	v_pk_mul_f32 v[38:39], v[40:41], v[46:47]
	v_pk_mul_f32 v[46:47], v[72:73], v[46:47]
	v_pk_fma_f32 v[38:39], v[72:73], v[76:77], v[38:39] neg_lo:[0,0,1] neg_hi:[0,0,1]
	v_pk_fma_f32 v[40:41], v[40:41], v[76:77], v[46:47]
	v_add_co_u32_e32 v46, vcc, 0x8000, v44
	s_nop 1
	v_addc_co_u32_e32 v47, vcc, 0, v45, vcc
	v_add_co_u32_e32 v72, vcc, 0xc000, v44
	v_mov_b32_e32 v46, v242
	v_mov_b32_e32 v47, v243
	s_nop 0
	v_addc_co_u32_e32 v73, vcc, 0, v45, vcc
	v_mov_b32_e32 v72, v244
	v_mov_b32_e32 v73, v245
	s_waitcnt vmcnt(1)
	v_mov_b32_e32 v76, v46
	s_waitcnt vmcnt(0)
	v_mov_b32_e32 v77, v72
	v_mov_b32_e32 v72, v47
	v_pk_mul_f32 v[46:47], v[42:43], v[72:73]
	s_nop 0
	v_pk_fma_f32 v[46:47], v[70:71], v[76:77], v[46:47] neg_lo:[0,0,1] neg_hi:[0,0,1]
	v_pk_mul_f32 v[70:71], v[70:71], v[72:73]
	s_nop 0
	v_pk_fma_f32 v[42:43], v[42:43], v[76:77], v[70:71]
	v_add_co_u32_e32 v70, vcc, s4, v44
	s_mov_b32 s4, 0x24000
	s_nop 0
	v_addc_co_u32_e32 v71, vcc, 0, v45, vcc
	v_add_co_u32_e32 v72, vcc, s4, v44
	v_mov_b32_e32 v70, v246
	v_mov_b32_e32 v71, v247
	s_nop 0
	v_addc_co_u32_e32 v73, vcc, 0, v45, vcc
	v_mov_b32_e32 v72, v248
	v_mov_b32_e32 v73, v249
	s_mov_b32 s4, 0x2c000
	s_waitcnt vmcnt(1)
	v_mov_b32_e32 v76, v70
	s_waitcnt vmcnt(0)
	v_mov_b32_e32 v77, v72
	v_mov_b32_e32 v72, v71
	v_pk_mul_f32 v[70:71], v[32:33], v[72:73]
	s_nop 0
	v_pk_fma_f32 v[70:71], v[68:69], v[76:77], v[70:71] neg_lo:[0,0,1] neg_hi:[0,0,1]
	v_pk_mul_f32 v[68:69], v[68:69], v[72:73]
	s_nop 0
	v_pk_fma_f32 v[32:33], v[32:33], v[76:77], v[68:69]
	v_add_co_u32_e32 v68, vcc, s4, v44
	s_mov_b32 s4, 0x28000
	s_nop 0
	v_addc_co_u32_e32 v69, vcc, 0, v45, vcc
	v_add_co_u32_e32 v44, vcc, s4, v44
	v_mov_b32_e32 v68, v250
	v_mov_b32_e32 v69, v251
	s_nop 0
	v_addc_co_u32_e32 v45, vcc, 0, v45, vcc
	v_mov_b32_e32 v44, v252
	v_mov_b32_e32 v45, v253
	s_waitcnt vmcnt(1)
	v_mov_b32_e32 v77, v69
	v_pk_mul_f32 v[34:35], v[34:35], v[68:69]
	v_mov_b32_e32 v73, v68
	s_waitcnt vmcnt(0)
	v_mov_b32_e32 v76, v45
	v_mov_b32_e32 v72, v44
	v_pk_mul_f32 v[76:77], v[36:37], v[76:77]
	v_mul_f32_e32 v36, v36, v44
	v_mul_f32_e32 v44, v66, v45
	v_mov_b32_e32 v37, v34
	v_mov_b32_e32 v45, v35
	v_pk_fma_f32 v[72:73], v[66:67], v[72:73], v[76:77] neg_lo:[0,0,1] neg_hi:[0,0,1]
	v_pk_add_f32 v[36:37], v[36:37], v[44:45]
	v_mov_b32_e32 v35, v73
	v_mov_b32_e32 v34, v37
	v_mov_b32_e32 v66, v72
	v_mov_b32_e32 v69, v71
	v_mov_b32_e32 v68, v70
	v_mov_b32_e32 v71, v47
	v_mov_b32_e32 v70, v46
	v_mov_b32_e32 v73, v39
	v_mov_b32_e32 v72, v38
